# hot-loop code placement: the six peeled GEMM K-loop heads aligned to 64 bytes (padding sits behind an unconditional branch)
# speedup vs baseline: 1.0064x; 1.0050x over previous
;     __device__ __forceinline__ const char* tile(const Unit& u, int t) const { return A + (size_t)u.pm * 2 * hstep() + (size_t)t * (BK * 2); }
;     __device__ __forceinline__ const char* tile(const Unit& u, int t) const { return U + (long)(t >> 2) * xoff + (size_t)u.pn * (1024 * 512) + (size_t)u.pm * 2 * hstep() + (size_t)(t & 3) * (BK * 2); }
; #define PG8_STAGE(bufoff, gbase, voff) do { _Pragma("unroll") for (int _i = 0; _i < 2; ++_i) \
;         __builtin_amdgcn_global_load_lds((const unsigned*)((const char*)(gbase) + (voff)[_i]), (PG8_LAS unsigned*)(lds + (bufoff) + ldsw + _i * 8192), 16, 0, 0); } while (0)
; #define PG8_LDA(dst, b, h) do { _Pragma("unroll") for (int m = 0; m < 4; ++m) _Pragma("unroll") for (int k = 0; k < 2; ++k) dst[m][k] = *(const PG8_LAS bf16x8*)(lds + PG8_SA(b, h) + aoff + m * 2048 + k * 1024); } while (0)
; #define PG8_LDB(dst, b, h) do { _Pragma("unroll") for (int n = 0; n < 2; ++n) _Pragma("unroll") for (int k = 0; k < 2; ++k) dst[n][k] = *(const PG8_LAS bf16x8*)(lds + PG8_SB(b, h) + boff + n * 2048 + k * 1024); } while (0)
; #define PG8_MMA(ai, bj, At, Bt) do { __builtin_amdgcn_s_setprio(1); _Pragma("unroll") for (int m = 0; m < 4; ++m) _Pragma("unroll") for (int n = 0; n < 2; ++n) _Pragma("unroll") for (int k = 0; k < 2; ++k) \
;         acc[ai][bj][m][n] = __builtin_amdgcn_mfma_f32_16x16x32_bf16(Bt[n][k], At[m][k], acc[ai][bj][m][n], 0, 0, 0); __builtin_amdgcn_s_setprio(0); } while (0)
; #define PG8_WAIT_V(n) asm volatile("s_waitcnt vmcnt(" #n ")" ::: "memory")
;     ...
;             const bool last = (t == nt - 2);
;             const char* a1 = AS.tile(cur, t + 1);
;             const char* a2 = last ? AS.tile(nu, 0) : AS.tile(cur, t + 2); const char* b2 = last ? nB : cB + (size_t)(t + 2) * kstep;
;             const char* a3 = last ? AS.tile(nu, 1) : AS.tile(cur, t + 3); const char* b3 = b2 + kstep;
;             PG8_LDB(B0, 0, 0); PG8_LDB(B1, 0, 1); PG8_SCHED; PG8_LDA(At, 0, 0); PG8_STAGE(PG8_SA(1, 1), a1 + hstepA, voffA);
;             PG8_WAIT_V(8); PG8_WAIT_L(0); PG8_BAR; PG8_MMA(0, 0, At, B0); PG8_MMA(0, 1, At, B1); PG8_BAR; PG8_SCHED;
;             PG8_LDA(At, 0, 1); PG8_STAGE(PG8_SB(0, 0), b2, voffB); PG8_STAGE(PG8_SB(0, 1), b2 + hstepB, voffB); PG8_STAGE(PG8_SA(0, 0), a2, voffA);
;             PG8_WAIT_V(8); PG8_WAIT_L(0); PG8_BAR; PG8_MMA(1, 0, At, B0); PG8_MMA(1, 1, At, B1); PG8_BAR; PG8_SCHED;
.Lpeel_380:
	s_add_u32 s28, s1, s2
	s_addc_u32 s29, s77, s3
	s_add_u32 s48, s28, 0x100
	s_addc_u32 s49, s29, 0
	s_add_u32 s46, s82, s2
	s_addc_u32 s47, s83, s3
	s_add_u32 s28, s28, 0x180
	s_addc_u32 s29, s29, 0
	s_add_i32 s85, 0, 0x10000
	s_add_i32 s88, 0, 0x14000
	v_add_u32_e32 v158, s85, v174
	v_add_u32_e32 v186, s88, v174
	ds_read_b128 v[132:135], v158
	ds_read_b128 v[136:139], v158 offset:1024
	ds_read_b128 v[140:143], v158 offset:2048
	ds_read_b128 v[158:161], v158 offset:3072
	ds_read_b128 v[162:165], v186
	ds_read_b128 v[166:169], v186 offset:1024
	ds_read_b128 v[182:185], v186 offset:2048
	ds_read_b128 v[186:189], v186 offset:3072
	s_cmpk_eq_i32 s2, 0x700
	s_cselect_b32 s29, s81, s29
	s_cselect_b32 s28, s80, s28
	s_cselect_b32 s47, s76, s47
	s_cselect_b32 s46, s75, s46
	s_cselect_b32 s49, s79, s49
	s_cselect_b32 s48, s78, s48
	v_lshl_add_u64 v[222:223], v[128:129], 0, s[2:3]
	s_add_i32 m0, s27, 0xc000
	ds_read_b128 v[190:193], v180
	ds_read_b128 v[194:197], v180 offset:1024
	ds_read_b128 v[198:201], v180 offset:2048
	ds_read_b128 v[204:207], v180 offset:3072
	ds_read_b128 v[218:221], v180 offset:4096
	ds_read_b128 v[238:241], v180 offset:5120
	ds_read_b128 v[242:245], v180 offset:6144
	ds_read_b128 v[246:249], v180 offset:7168
	global_load_lds_dwordx4 v[222:223], off
	v_lshl_add_u64 v[222:223], v[130:131], 0, s[2:3]
	s_add_i32 m0, s27, 0xe000
	s_nop 0
	global_load_lds_dwordx4 v[222:223], off
	s_waitcnt vmcnt(8)
	s_waitcnt lgkmcnt(0)
	s_barrier
	s_setprio 1
	s_waitcnt lgkmcnt(0)
	v_mfma_f32_16x16x32_bf16 v[124:127], v[132:135], v[190:193], 0
	v_mfma_f32_16x16x32_bf16 v[120:123], v[140:143], v[190:193], 0
	v_mfma_f32_16x16x32_bf16 v[108:111], v[132:135], v[198:201], 0
	v_mfma_f32_16x16x32_bf16 v[104:107], v[140:143], v[198:201], 0
	v_mfma_f32_16x16x32_bf16 v[92:95], v[132:135], v[218:221], 0
	v_mfma_f32_16x16x32_bf16 v[88:91], v[140:143], v[218:221], 0
	v_mfma_f32_16x16x32_bf16 v[76:79], v[132:135], v[242:245], 0
	v_mfma_f32_16x16x32_bf16 v[72:75], v[140:143], v[242:245], 0
	v_mfma_f32_16x16x32_bf16 v[124:127], v[136:139], v[194:197], v[124:127]
	v_mfma_f32_16x16x32_bf16 v[120:123], v[158:161], v[194:197], v[120:123]
	v_mfma_f32_16x16x32_bf16 v[108:111], v[136:139], v[204:207], v[108:111]
	v_mfma_f32_16x16x32_bf16 v[104:107], v[158:161], v[204:207], v[104:107]
	v_mfma_f32_16x16x32_bf16 v[92:95], v[136:139], v[238:241], v[92:95]
	v_mfma_f32_16x16x32_bf16 v[88:91], v[158:161], v[238:241], v[88:91]
	v_mfma_f32_16x16x32_bf16 v[76:79], v[136:139], v[246:249], v[76:79]
	v_mfma_f32_16x16x32_bf16 v[72:75], v[158:161], v[246:249], v[72:75]
	s_setprio 0
	s_setprio 1
	v_mfma_f32_16x16x32_bf16 v[116:119], v[162:165], v[190:193], 0
	v_mfma_f32_16x16x32_bf16 v[112:115], v[182:185], v[190:193], 0
	v_mfma_f32_16x16x32_bf16 v[100:103], v[162:165], v[198:201], 0
	v_mfma_f32_16x16x32_bf16 v[96:99], v[182:185], v[198:201], 0
	v_mfma_f32_16x16x32_bf16 v[84:87], v[162:165], v[218:221], 0
	v_mfma_f32_16x16x32_bf16 v[80:83], v[182:185], v[218:221], 0
	v_mfma_f32_16x16x32_bf16 v[68:71], v[162:165], v[242:245], 0
	v_mfma_f32_16x16x32_bf16 v[64:67], v[182:185], v[242:245], 0
	v_mfma_f32_16x16x32_bf16 v[116:119], v[166:169], v[194:197], v[116:119]
	v_mfma_f32_16x16x32_bf16 v[112:115], v[186:189], v[194:197], v[112:115]
	v_mfma_f32_16x16x32_bf16 v[100:103], v[166:169], v[204:207], v[100:103]
	v_mfma_f32_16x16x32_bf16 v[96:99], v[186:189], v[204:207], v[96:99]
	v_mfma_f32_16x16x32_bf16 v[84:87], v[166:169], v[238:241], v[84:87]
	v_mfma_f32_16x16x32_bf16 v[80:83], v[186:189], v[238:241], v[80:83]
	v_mfma_f32_16x16x32_bf16 v[68:71], v[166:169], v[246:249], v[68:71]
	v_mfma_f32_16x16x32_bf16 v[64:67], v[186:189], v[246:249], v[64:67]
	s_setprio 0
	s_barrier
	s_add_i32 s85, s85, s52
	v_lshl_add_u64 v[222:223], s[46:47], 0, v[146:147]
	s_mov_b32 m0, s85
	ds_read_b128 v[190:193], v180 offset:16384
	ds_read_b128 v[194:197], v180 offset:17408
	ds_read_b128 v[198:201], v180 offset:18432
	ds_read_b128 v[204:207], v180 offset:19456
	ds_read_b128 v[218:221], v180 offset:20480
	ds_read_b128 v[238:241], v180 offset:21504
	ds_read_b128 v[242:245], v180 offset:22528
	ds_read_b128 v[246:249], v180 offset:23552
	global_load_lds_dwordx4 v[222:223], off
	s_add_i32 m0, s85, 0x2000
	s_add_u32 s86, s46, 0x40000
	v_lshl_add_u64 v[224:225], s[46:47], 0, v[150:151]
	s_addc_u32 s87, s47, 0
	s_add_i32 s85, s88, s52
	global_load_lds_dwordx4 v[224:225], off
	v_lshl_add_u64 v[250:251], s[86:87], 0, v[146:147]
	s_mov_b32 m0, s85
	s_nop 0
	global_load_lds_dwordx4 v[250:251], off
	v_lshl_add_u64 v[250:251], s[86:87], 0, v[150:151]
	s_add_i32 m0, s85, 0x2000
	s_nop 0
	global_load_lds_dwordx4 v[250:251], off
	v_lshl_add_u64 v[250:251], s[48:49], 0, v[144:145]
	s_mov_b32 m0, s27
	s_nop 0
	global_load_lds_dwordx4 v[250:251], off
	v_lshl_add_u64 v[250:251], s[48:49], 0, v[148:149]
	s_mov_b32 m0, s57
	s_nop 0
	global_load_lds_dwordx4 v[250:251], off
	s_waitcnt vmcnt(8)
	s_waitcnt lgkmcnt(0)
	s_barrier
; #define PG8_STAGE(bufoff, gbase, voff) do { _Pragma("unroll") for (int _i = 0; _i < 2; ++_i) \
;         __builtin_amdgcn_global_load_lds((const unsigned*)((const char*)(gbase) + (voff)[_i]), (PG8_LAS unsigned*)(lds + (bufoff) + ldsw + _i * 8192), 16, 0, 0); } while (0)
; #define PG8_LDA(dst, b, h) do { _Pragma("unroll") for (int m = 0; m < 4; ++m) _Pragma("unroll") for (int k = 0; k < 2; ++k) dst[m][k] = *(const PG8_LAS bf16x8*)(lds + PG8_SA(b, h) + aoff + m * 2048 + k * 1024); } while (0)
; #define PG8_LDB(dst, b, h) do { _Pragma("unroll") for (int n = 0; n < 2; ++n) _Pragma("unroll") for (int k = 0; k < 2; ++k) dst[n][k] = *(const PG8_LAS bf16x8*)(lds + PG8_SB(b, h) + boff + n * 2048 + k * 1024); } while (0)
; #define PG8_MMA(ai, bj, At, Bt) do { __builtin_amdgcn_s_setprio(1); _Pragma("unroll") for (int m = 0; m < 4; ++m) _Pragma("unroll") for (int n = 0; n < 2; ++n) _Pragma("unroll") for (int k = 0; k < 2; ++k) \
;         acc[ai][bj][m][n] = __builtin_amdgcn_mfma_f32_16x16x32_bf16(Bt[n][k], At[m][k], acc[ai][bj][m][n], 0, 0, 0); __builtin_amdgcn_s_setprio(0); } while (0)
; #define PG8_WAIT_V(n) asm volatile("s_waitcnt vmcnt(" #n ")" ::: "memory")
; #define PG8_WAIT_L(n) asm volatile("s_waitcnt lgkmcnt(" #n ")" ::: "memory")
; #define PG8_BAR __builtin_amdgcn_s_barrier()
; #define PG8_SCHED __builtin_amdgcn_sched_barrier(0)
;     ...
;             PG8_WAIT_V(8); PG8_WAIT_L(0); PG8_BAR; PG8_MMA(1, 0, At, B0); PG8_MMA(1, 1, At, B1); PG8_BAR; PG8_SCHED;
;             PG8_LDB(B0, 1, 0); PG8_LDB(B1, 1, 1); PG8_SCHED; PG8_LDA(At, 1, 0); PG8_STAGE(PG8_SA(0, 1), a2 + hstepA, voffA);
;             PG8_WAIT_V(8); PG8_WAIT_L(0); PG8_BAR; PG8_MMA(0, 0, At, B0); PG8_MMA(0, 1, At, B1); PG8_BAR; PG8_SCHED;
;             PG8_LDA(At, 1, 1); PG8_STAGE(PG8_SB(1, 0), b3, voffB); PG8_STAGE(PG8_SB(1, 1), b3 + hstepB, voffB); PG8_STAGE(PG8_SA(1, 0), a3, voffA);
	s_setprio 1
	s_waitcnt lgkmcnt(0)
	v_mfma_f32_16x16x32_bf16 v[60:63], v[132:135], v[190:193], 0
	v_mfma_f32_16x16x32_bf16 v[56:59], v[140:143], v[190:193], 0
	v_mfma_f32_16x16x32_bf16 v[44:47], v[132:135], v[198:201], 0
	v_mfma_f32_16x16x32_bf16 v[40:43], v[140:143], v[198:201], 0
	v_mfma_f32_16x16x32_bf16 v[28:31], v[132:135], v[218:221], 0
	v_mfma_f32_16x16x32_bf16 v[24:27], v[140:143], v[218:221], 0
	v_mfma_f32_16x16x32_bf16 v[12:15], v[132:135], v[242:245], 0
	v_mfma_f32_16x16x32_bf16 v[8:11], v[140:143], v[242:245], 0
	v_mfma_f32_16x16x32_bf16 v[60:63], v[136:139], v[194:197], v[60:63]
	v_mfma_f32_16x16x32_bf16 v[56:59], v[158:161], v[194:197], v[56:59]
	v_mfma_f32_16x16x32_bf16 v[44:47], v[136:139], v[204:207], v[44:47]
	v_mfma_f32_16x16x32_bf16 v[40:43], v[158:161], v[204:207], v[40:43]
	v_mfma_f32_16x16x32_bf16 v[28:31], v[136:139], v[238:241], v[28:31]
	v_mfma_f32_16x16x32_bf16 v[24:27], v[158:161], v[238:241], v[24:27]
	v_mfma_f32_16x16x32_bf16 v[12:15], v[136:139], v[246:249], v[12:15]
	v_mfma_f32_16x16x32_bf16 v[8:11], v[158:161], v[246:249], v[8:11]
	s_setprio 0
	s_setprio 1
	v_mfma_f32_16x16x32_bf16 v[52:55], v[162:165], v[190:193], 0
	v_mfma_f32_16x16x32_bf16 v[48:51], v[182:185], v[190:193], 0
	v_mfma_f32_16x16x32_bf16 v[36:39], v[162:165], v[198:201], 0
	v_mfma_f32_16x16x32_bf16 v[32:35], v[182:185], v[198:201], 0
	v_mfma_f32_16x16x32_bf16 v[20:23], v[162:165], v[218:221], 0
	v_mfma_f32_16x16x32_bf16 v[16:19], v[182:185], v[218:221], 0
	v_mfma_f32_16x16x32_bf16 v[4:7], v[162:165], v[242:245], 0
	v_mfma_f32_16x16x32_bf16 v[0:3], v[182:185], v[242:245], 0
	v_mfma_f32_16x16x32_bf16 v[52:55], v[166:169], v[194:197], v[52:55]
	v_mfma_f32_16x16x32_bf16 v[48:51], v[186:189], v[194:197], v[48:51]
	v_mfma_f32_16x16x32_bf16 v[36:39], v[166:169], v[204:207], v[36:39]
	v_mfma_f32_16x16x32_bf16 v[32:35], v[186:189], v[204:207], v[32:35]
	v_mfma_f32_16x16x32_bf16 v[20:23], v[166:169], v[238:241], v[20:23]
	v_mfma_f32_16x16x32_bf16 v[16:19], v[186:189], v[238:241], v[16:19]
	v_mfma_f32_16x16x32_bf16 v[4:7], v[166:169], v[246:249], v[4:7]
	v_mfma_f32_16x16x32_bf16 v[0:3], v[186:189], v[246:249], v[0:3]
	s_setprio 0
	s_barrier
	s_add_i32 s85, 0, 0x18000
	s_add_i32 s86, 0, 0x1c000
	v_add_u32_e32 v158, s85, v174
	v_add_u32_e32 v186, s86, v174
	ds_read_b128 v[132:135], v158
	ds_read_b128 v[136:139], v158 offset:1024
	ds_read_b128 v[140:143], v158 offset:2048
	ds_read_b128 v[158:161], v158 offset:3072
	ds_read_b128 v[162:165], v186
	ds_read_b128 v[166:169], v186 offset:1024
	ds_read_b128 v[182:185], v186 offset:2048
	ds_read_b128 v[186:189], v186 offset:3072
	s_add_u32 s48, s48, 0x40000
	s_addc_u32 s49, s49, 0
	s_mov_b32 m0, s58
	v_lshl_add_u64 v[250:251], s[48:49], 0, v[144:145]
	ds_read_b128 v[190:193], v180 offset:32768
	ds_read_b128 v[194:197], v180 offset:33792
	ds_read_b128 v[198:201], v180 offset:34816
	ds_read_b128 v[204:207], v180 offset:35840
	ds_read_b128 v[218:221], v180 offset:36864
	ds_read_b128 v[238:241], v180 offset:37888
	ds_read_b128 v[242:245], v180 offset:38912
	ds_read_b128 v[246:249], v180 offset:39936
	global_load_lds_dwordx4 v[250:251], off
	v_lshl_add_u64 v[250:251], s[48:49], 0, v[148:149]
	s_mov_b32 m0, s59
	s_nop 0
	global_load_lds_dwordx4 v[250:251], off
	s_waitcnt vmcnt(8)
	s_waitcnt lgkmcnt(0)
	s_barrier
	s_setprio 1
	s_waitcnt lgkmcnt(0)
	v_mfma_f32_16x16x32_bf16 v[124:127], v[132:135], v[190:193], v[124:127]
	v_mfma_f32_16x16x32_bf16 v[120:123], v[140:143], v[190:193], v[120:123]
	v_mfma_f32_16x16x32_bf16 v[108:111], v[132:135], v[198:201], v[108:111]
	v_mfma_f32_16x16x32_bf16 v[104:107], v[140:143], v[198:201], v[104:107]
	v_mfma_f32_16x16x32_bf16 v[92:95], v[132:135], v[218:221], v[92:95]
	v_mfma_f32_16x16x32_bf16 v[88:91], v[140:143], v[218:221], v[88:91]
	v_mfma_f32_16x16x32_bf16 v[76:79], v[132:135], v[242:245], v[76:79]
	v_mfma_f32_16x16x32_bf16 v[72:75], v[140:143], v[242:245], v[72:75]
	v_mfma_f32_16x16x32_bf16 v[124:127], v[136:139], v[194:197], v[124:127]
	v_mfma_f32_16x16x32_bf16 v[120:123], v[158:161], v[194:197], v[120:123]
	v_mfma_f32_16x16x32_bf16 v[108:111], v[136:139], v[204:207], v[108:111]
	v_mfma_f32_16x16x32_bf16 v[104:107], v[158:161], v[204:207], v[104:107]
	v_mfma_f32_16x16x32_bf16 v[92:95], v[136:139], v[238:241], v[92:95]
	v_mfma_f32_16x16x32_bf16 v[88:91], v[158:161], v[238:241], v[88:91]
	v_mfma_f32_16x16x32_bf16 v[76:79], v[136:139], v[246:249], v[76:79]
	v_mfma_f32_16x16x32_bf16 v[72:75], v[158:161], v[246:249], v[72:75]
	s_setprio 0
	s_setprio 1
	v_mfma_f32_16x16x32_bf16 v[116:119], v[162:165], v[190:193], v[116:119]
	v_mfma_f32_16x16x32_bf16 v[112:115], v[182:185], v[190:193], v[112:115]
	v_mfma_f32_16x16x32_bf16 v[100:103], v[162:165], v[198:201], v[100:103]
	v_mfma_f32_16x16x32_bf16 v[96:99], v[182:185], v[198:201], v[96:99]
	v_mfma_f32_16x16x32_bf16 v[84:87], v[162:165], v[218:221], v[84:87]
	v_mfma_f32_16x16x32_bf16 v[80:83], v[182:185], v[218:221], v[80:83]
	v_mfma_f32_16x16x32_bf16 v[68:71], v[162:165], v[242:245], v[68:71]
	v_mfma_f32_16x16x32_bf16 v[64:67], v[182:185], v[242:245], v[64:67]
	v_mfma_f32_16x16x32_bf16 v[116:119], v[166:169], v[194:197], v[116:119]
	v_mfma_f32_16x16x32_bf16 v[112:115], v[186:189], v[194:197], v[112:115]
	v_mfma_f32_16x16x32_bf16 v[100:103], v[166:169], v[204:207], v[100:103]
	v_mfma_f32_16x16x32_bf16 v[96:99], v[186:189], v[204:207], v[96:99]
	v_mfma_f32_16x16x32_bf16 v[84:87], v[166:169], v[238:241], v[84:87]
	v_mfma_f32_16x16x32_bf16 v[80:83], v[186:189], v[238:241], v[80:83]
	v_mfma_f32_16x16x32_bf16 v[68:71], v[166:169], v[246:249], v[68:71]
	v_mfma_f32_16x16x32_bf16 v[64:67], v[186:189], v[246:249], v[64:67]
	s_setprio 0
	s_barrier
; #define PG8_STAGE(bufoff, gbase, voff) do { _Pragma("unroll") for (int _i = 0; _i < 2; ++_i) \
;         __builtin_amdgcn_global_load_lds((const unsigned*)((const char*)(gbase) + (voff)[_i]), (PG8_LAS unsigned*)(lds + (bufoff) + ldsw + _i * 8192), 16, 0, 0); } while (0)
; #define PG8_LDA(dst, b, h) do { _Pragma("unroll") for (int m = 0; m < 4; ++m) _Pragma("unroll") for (int k = 0; k < 2; ++k) dst[m][k] = *(const PG8_LAS bf16x8*)(lds + PG8_SA(b, h) + aoff + m * 2048 + k * 1024); } while (0)
; #define PG8_MMA(ai, bj, At, Bt) do { __builtin_amdgcn_s_setprio(1); _Pragma("unroll") for (int m = 0; m < 4; ++m) _Pragma("unroll") for (int n = 0; n < 2; ++n) _Pragma("unroll") for (int k = 0; k < 2; ++k) \
;         acc[ai][bj][m][n] = __builtin_amdgcn_mfma_f32_16x16x32_bf16(Bt[n][k], At[m][k], acc[ai][bj][m][n], 0, 0, 0); __builtin_amdgcn_s_setprio(0); } while (0)
; #define PG8_WAIT_V(n) asm volatile("s_waitcnt vmcnt(" #n ")" ::: "memory")
; #define PG8_WAIT_L(n) asm volatile("s_waitcnt lgkmcnt(" #n ")" ::: "memory")
; #define PG8_BAR __builtin_amdgcn_s_barrier()
; #define PG8_SCHED __builtin_amdgcn_sched_barrier(0)
;     ...
;         for (int t = 0; t < nt; t += 2) {
;     ...
;             PG8_LDA(At, 1, 1); PG8_STAGE(PG8_SB(1, 0), b3, voffB); PG8_STAGE(PG8_SB(1, 1), b3 + hstepB, voffB); PG8_STAGE(PG8_SA(1, 0), a3, voffA);
;             PG8_WAIT_V(8); PG8_WAIT_L(0); PG8_BAR; PG8_MMA(1, 0, At, B0); PG8_MMA(1, 1, At, B1); PG8_BAR; PG8_SCHED;
;         }
	s_add_i32 s48, s85, s52
	v_lshl_add_u64 v[222:223], v[222:223], 0, s[90:91]
	s_mov_b32 m0, s48
	ds_read_b128 v[190:193], v180 offset:49152
	ds_read_b128 v[194:197], v180 offset:50176
	ds_read_b128 v[198:201], v180 offset:51200
	ds_read_b128 v[204:207], v180 offset:52224
	ds_read_b128 v[218:221], v180 offset:53248
	ds_read_b128 v[238:241], v180 offset:54272
	ds_read_b128 v[242:245], v180 offset:55296
	ds_read_b128 v[246:249], v180 offset:56320
	global_load_lds_dwordx4 v[222:223], off
	s_add_i32 m0, s48, 0x2000
	s_add_u32 s46, s46, 0x40080
	v_lshl_add_u64 v[222:223], v[224:225], 0, s[90:91]
	s_addc_u32 s47, s47, 0
	s_add_i32 s48, s86, s52
	global_load_lds_dwordx4 v[222:223], off
	v_lshl_add_u64 v[222:223], s[46:47], 0, v[146:147]
	s_mov_b32 m0, s48
	s_nop 0
	global_load_lds_dwordx4 v[222:223], off
	v_lshl_add_u64 v[222:223], s[46:47], 0, v[150:151]
	s_add_i32 m0, s48, 0x2000
	s_nop 0
	global_load_lds_dwordx4 v[222:223], off
	v_lshl_add_u64 v[222:223], s[28:29], 0, v[144:145]
	s_mov_b32 m0, s60
	s_nop 0
	global_load_lds_dwordx4 v[222:223], off
	v_lshl_add_u64 v[222:223], s[28:29], 0, v[148:149]
	s_mov_b32 m0, s61
	s_nop 0
	global_load_lds_dwordx4 v[222:223], off
	s_waitcnt vmcnt(8)
	s_waitcnt lgkmcnt(0)
	s_barrier
	s_setprio 1
	s_waitcnt lgkmcnt(0)
	v_mfma_f32_16x16x32_bf16 v[60:63], v[132:135], v[190:193], v[60:63]
	v_mfma_f32_16x16x32_bf16 v[56:59], v[140:143], v[190:193], v[56:59]
	v_mfma_f32_16x16x32_bf16 v[44:47], v[132:135], v[198:201], v[44:47]
	v_mfma_f32_16x16x32_bf16 v[40:43], v[140:143], v[198:201], v[40:43]
	v_mfma_f32_16x16x32_bf16 v[28:31], v[132:135], v[218:221], v[28:31]
	v_mfma_f32_16x16x32_bf16 v[24:27], v[140:143], v[218:221], v[24:27]
	v_mfma_f32_16x16x32_bf16 v[12:15], v[132:135], v[242:245], v[12:15]
	v_mfma_f32_16x16x32_bf16 v[8:11], v[140:143], v[242:245], v[8:11]
	v_mfma_f32_16x16x32_bf16 v[60:63], v[136:139], v[194:197], v[60:63]
	v_mfma_f32_16x16x32_bf16 v[56:59], v[158:161], v[194:197], v[56:59]
	v_mfma_f32_16x16x32_bf16 v[44:47], v[136:139], v[204:207], v[44:47]
	v_mfma_f32_16x16x32_bf16 v[40:43], v[158:161], v[204:207], v[40:43]
	v_mfma_f32_16x16x32_bf16 v[28:31], v[136:139], v[238:241], v[28:31]
	v_mfma_f32_16x16x32_bf16 v[24:27], v[158:161], v[238:241], v[24:27]
	v_mfma_f32_16x16x32_bf16 v[12:15], v[136:139], v[246:249], v[12:15]
	v_mfma_f32_16x16x32_bf16 v[8:11], v[158:161], v[246:249], v[8:11]
	s_setprio 0
	s_setprio 1
	v_mfma_f32_16x16x32_bf16 v[52:55], v[162:165], v[190:193], v[52:55]
	v_mfma_f32_16x16x32_bf16 v[48:51], v[182:185], v[190:193], v[48:51]
	v_mfma_f32_16x16x32_bf16 v[36:39], v[162:165], v[198:201], v[36:39]
	v_mfma_f32_16x16x32_bf16 v[32:35], v[182:185], v[198:201], v[32:35]
	v_mfma_f32_16x16x32_bf16 v[20:23], v[162:165], v[218:221], v[20:23]
	v_mfma_f32_16x16x32_bf16 v[16:19], v[182:185], v[218:221], v[16:19]
	v_mfma_f32_16x16x32_bf16 v[4:7], v[162:165], v[242:245], v[4:7]
	v_mfma_f32_16x16x32_bf16 v[0:3], v[182:185], v[242:245], v[0:3]
	v_mfma_f32_16x16x32_bf16 v[52:55], v[166:169], v[194:197], v[52:55]
	v_mfma_f32_16x16x32_bf16 v[48:51], v[186:189], v[194:197], v[48:51]
	v_mfma_f32_16x16x32_bf16 v[36:39], v[166:169], v[204:207], v[36:39]
	v_mfma_f32_16x16x32_bf16 v[32:35], v[186:189], v[204:207], v[32:35]
	v_mfma_f32_16x16x32_bf16 v[20:23], v[166:169], v[238:241], v[20:23]
	v_mfma_f32_16x16x32_bf16 v[16:19], v[186:189], v[238:241], v[16:19]
	v_mfma_f32_16x16x32_bf16 v[4:7], v[166:169], v[246:249], v[4:7]
	v_mfma_f32_16x16x32_bf16 v[0:3], v[186:189], v[246:249], v[0:3]
	s_setprio 0
	s_barrier
	s_add_i32 s84, s84, 2
	s_add_u32 s2, s2, 0x100
	s_addc_u32 s3, s3, 0
	s_cmp_gt_u32 s84, 13
	s_cbranch_scc0 .LBB0_380
	s_branch .Lpeel_exit_380
	.p2alignl 6, 3212836864

;     __device__ __forceinline__ const char* tile(const Unit& u, int t) const { return A + (size_t)u.pm * 2 * hstep() + (size_t)t * (BK * 2); }
;     __device__ __forceinline__ const char* tile(const Unit& u, int t) const { return U + (long)(t >> 2) * xoff + (size_t)u.pn * (1024 * 512) + (size_t)u.pm * 2 * hstep() + (size_t)(t & 3) * (BK * 2); }
; #define PG8_STAGE(bufoff, gbase, voff) do { _Pragma("unroll") for (int _i = 0; _i < 2; ++_i) \
;         __builtin_amdgcn_global_load_lds((const unsigned*)((const char*)(gbase) + (voff)[_i]), (PG8_LAS unsigned*)(lds + (bufoff) + ldsw + _i * 8192), 16, 0, 0); } while (0)
; #define PG8_LDA(dst, b, h) do { _Pragma("unroll") for (int m = 0; m < 4; ++m) _Pragma("unroll") for (int k = 0; k < 2; ++k) dst[m][k] = *(const PG8_LAS bf16x8*)(lds + PG8_SA(b, h) + aoff + m * 2048 + k * 1024); } while (0)
; #define PG8_LDB(dst, b, h) do { _Pragma("unroll") for (int n = 0; n < 2; ++n) _Pragma("unroll") for (int k = 0; k < 2; ++k) dst[n][k] = *(const PG8_LAS bf16x8*)(lds + PG8_SB(b, h) + boff + n * 2048 + k * 1024); } while (0)
; #define PG8_MMA(ai, bj, At, Bt) do { __builtin_amdgcn_s_setprio(1); _Pragma("unroll") for (int m = 0; m < 4; ++m) _Pragma("unroll") for (int n = 0; n < 2; ++n) _Pragma("unroll") for (int k = 0; k < 2; ++k) \
;         acc[ai][bj][m][n] = __builtin_amdgcn_mfma_f32_16x16x32_bf16(Bt[n][k], At[m][k], acc[ai][bj][m][n], 0, 0, 0); __builtin_amdgcn_s_setprio(0); } while (0)
; #define PG8_WAIT_V(n) asm volatile("s_waitcnt vmcnt(" #n ")" ::: "memory")
;     ...
;             const bool last = (t == nt - 2);
;             const char* a1 = AS.tile(cur, t + 1);
;             const char* a2 = last ? AS.tile(nu, 0) : AS.tile(cur, t + 2); const char* b2 = last ? nB : cB + (size_t)(t + 2) * kstep;
;             const char* a3 = last ? AS.tile(nu, 1) : AS.tile(cur, t + 3); const char* b3 = b2 + kstep;
;             PG8_LDB(B0, 0, 0); PG8_LDB(B1, 0, 1); PG8_SCHED; PG8_LDA(At, 0, 0); PG8_STAGE(PG8_SA(1, 1), a1 + hstepA, voffA);
;             PG8_WAIT_V(8); PG8_WAIT_L(0); PG8_BAR; PG8_MMA(0, 0, At, B0); PG8_MMA(0, 1, At, B1); PG8_BAR; PG8_SCHED;
;             PG8_LDA(At, 0, 1); PG8_STAGE(PG8_SB(0, 0), b2, voffB); PG8_STAGE(PG8_SB(0, 1), b2 + hstepB, voffB); PG8_STAGE(PG8_SA(0, 0), a2, voffA);
;             PG8_WAIT_V(8); PG8_WAIT_L(0); PG8_BAR; PG8_MMA(1, 0, At, B0); PG8_MMA(1, 1, At, B1); PG8_BAR; PG8_SCHED;
.Lpeel_451:
	s_add_u32 s20, s61, s18
	s_addc_u32 s21, s64, s19
	s_add_u32 s26, s20, 0x3600100
	s_addc_u32 s27, s21, 0
	s_add_u32 s24, s65, s18
	s_addc_u32 s25, s66, s19
	s_add_u32 s20, s20, 0x3600180
	s_addc_u32 s21, s21, 0
	s_add_i32 s68, 0, 0x10000
	s_add_i32 s70, 0, 0x14000
	v_add_u32_e32 v144, s68, v203
	v_add_u32_e32 v174, s70, v203
	ds_read_b128 v[132:135], v144
	ds_read_b128 v[136:139], v144 offset:1024
	ds_read_b128 v[140:143], v144 offset:2048
	ds_read_b128 v[144:147], v144 offset:3072
	ds_read_b128 v[148:151], v174
	ds_read_b128 v[152:155], v174 offset:1024
	ds_read_b128 v[170:173], v174 offset:2048
	ds_read_b128 v[174:177], v174 offset:3072
	s_cmpk_eq_i32 s18, 0x700
	s_cselect_b32 s21, s60, s21
	s_cselect_b32 s20, s59, s20
	s_cselect_b32 s25, s57, s25
	s_cselect_b32 s24, s56, s24
	s_cselect_b32 s27, s58, s27
	s_cselect_b32 s26, s3, s26
	v_lshl_add_u64 v[238:239], v[112:113], 0, s[18:19]
	s_add_i32 m0, s35, 0xc000
	ds_read_b128 v[178:181], v211
	ds_read_b128 v[182:185], v211 offset:1024
	ds_read_b128 v[186:189], v211 offset:2048
	ds_read_b128 v[190:193], v211 offset:3072
	ds_read_b128 v[194:197], v211 offset:4096
	ds_read_b128 v[198:201], v211 offset:5120
	ds_read_b128 v[218:221], v211 offset:6144
	ds_read_b128 v[222:225], v211 offset:7168
	global_load_lds_dwordx4 v[238:239], off
	v_lshl_add_u64 v[238:239], v[114:115], 0, s[18:19]
	s_add_i32 m0, s35, 0xe000
	s_nop 0
	global_load_lds_dwordx4 v[238:239], off
	s_waitcnt vmcnt(24)
	s_waitcnt lgkmcnt(0)
	s_barrier
	s_setprio 1
	s_waitcnt lgkmcnt(0)
	v_mfma_f32_16x16x32_bf16 v[120:123], v[132:135], v[178:181], 0
	v_mfma_f32_16x16x32_bf16 v[116:119], v[140:143], v[178:181], 0
	v_mfma_f32_16x16x32_bf16 v[108:111], v[132:135], v[186:189], 0
	v_mfma_f32_16x16x32_bf16 v[104:107], v[140:143], v[186:189], 0
	v_mfma_f32_16x16x32_bf16 v[92:95], v[132:135], v[194:197], 0
	v_mfma_f32_16x16x32_bf16 v[88:91], v[140:143], v[194:197], 0
	v_mfma_f32_16x16x32_bf16 v[76:79], v[132:135], v[218:221], 0
	v_mfma_f32_16x16x32_bf16 v[72:75], v[140:143], v[218:221], 0
	v_mfma_f32_16x16x32_bf16 v[120:123], v[136:139], v[182:185], v[120:123]
	v_mfma_f32_16x16x32_bf16 v[116:119], v[144:147], v[182:185], v[116:119]
	v_mfma_f32_16x16x32_bf16 v[108:111], v[136:139], v[190:193], v[108:111]
	v_mfma_f32_16x16x32_bf16 v[104:107], v[144:147], v[190:193], v[104:107]
	v_mfma_f32_16x16x32_bf16 v[92:95], v[136:139], v[198:201], v[92:95]
	v_mfma_f32_16x16x32_bf16 v[88:91], v[144:147], v[198:201], v[88:91]
	v_mfma_f32_16x16x32_bf16 v[76:79], v[136:139], v[222:225], v[76:79]
	v_mfma_f32_16x16x32_bf16 v[72:75], v[144:147], v[222:225], v[72:75]
	s_setprio 0
	s_setprio 1
	v_mfma_f32_16x16x32_bf16 v[128:131], v[148:151], v[178:181], 0
	v_mfma_f32_16x16x32_bf16 v[124:127], v[170:173], v[178:181], 0
	v_mfma_f32_16x16x32_bf16 v[100:103], v[148:151], v[186:189], 0
	v_mfma_f32_16x16x32_bf16 v[96:99], v[170:173], v[186:189], 0
	v_mfma_f32_16x16x32_bf16 v[84:87], v[148:151], v[194:197], 0
	v_mfma_f32_16x16x32_bf16 v[80:83], v[170:173], v[194:197], 0
	v_mfma_f32_16x16x32_bf16 v[68:71], v[148:151], v[218:221], 0
	v_mfma_f32_16x16x32_bf16 v[64:67], v[170:173], v[218:221], 0
	v_mfma_f32_16x16x32_bf16 v[128:131], v[152:155], v[182:185], v[128:131]
	v_mfma_f32_16x16x32_bf16 v[124:127], v[174:177], v[182:185], v[124:127]
	v_mfma_f32_16x16x32_bf16 v[100:103], v[152:155], v[190:193], v[100:103]
	v_mfma_f32_16x16x32_bf16 v[96:99], v[174:177], v[190:193], v[96:99]
	v_mfma_f32_16x16x32_bf16 v[84:87], v[152:155], v[198:201], v[84:87]
	v_mfma_f32_16x16x32_bf16 v[80:83], v[174:177], v[198:201], v[80:83]
	v_mfma_f32_16x16x32_bf16 v[68:71], v[152:155], v[222:225], v[68:71]
	v_mfma_f32_16x16x32_bf16 v[64:67], v[174:177], v[222:225], v[64:67]
	s_setprio 0
	s_barrier
	s_add_i32 s68, s68, s31
	v_lshl_add_u64 v[238:239], s[24:25], 0, v[208:209]
	s_mov_b32 m0, s68
	ds_read_b128 v[178:181], v211 offset:16384
	ds_read_b128 v[182:185], v211 offset:17408
	ds_read_b128 v[186:189], v211 offset:18432
	ds_read_b128 v[190:193], v211 offset:19456
	ds_read_b128 v[194:197], v211 offset:20480
	ds_read_b128 v[198:201], v211 offset:21504
	ds_read_b128 v[218:221], v211 offset:22528
	ds_read_b128 v[222:225], v211 offset:23552
	global_load_lds_dwordx4 v[238:239], off
	s_add_i32 m0, s68, 0x2000
	s_add_u32 s68, s24, 0x40000
	v_lshl_add_u64 v[240:241], s[24:25], 0, v[156:157]
	s_addc_u32 s69, s25, 0
	s_add_i32 s70, s70, s31
	global_load_lds_dwordx4 v[240:241], off
	v_lshl_add_u64 v[242:243], s[68:69], 0, v[208:209]
	s_mov_b32 m0, s70
	s_nop 0
	global_load_lds_dwordx4 v[242:243], off
	v_lshl_add_u64 v[242:243], s[68:69], 0, v[156:157]
	s_add_i32 m0, s70, 0x2000
	s_nop 0
	global_load_lds_dwordx4 v[242:243], off
	v_lshl_add_u64 v[242:243], s[26:27], 0, v[160:161]
	s_mov_b32 m0, s35
	s_nop 0
	global_load_lds_dwordx4 v[242:243], off
	v_lshl_add_u64 v[242:243], s[26:27], 0, v[158:159]
	s_mov_b32 m0, s44
	s_nop 0
	global_load_lds_dwordx4 v[242:243], off
	s_waitcnt vmcnt(8)
	s_waitcnt lgkmcnt(0)
	s_barrier
; #define PG8_STAGE(bufoff, gbase, voff) do { _Pragma("unroll") for (int _i = 0; _i < 2; ++_i) \
;         __builtin_amdgcn_global_load_lds((const unsigned*)((const char*)(gbase) + (voff)[_i]), (PG8_LAS unsigned*)(lds + (bufoff) + ldsw + _i * 8192), 16, 0, 0); } while (0)
; #define PG8_LDA(dst, b, h) do { _Pragma("unroll") for (int m = 0; m < 4; ++m) _Pragma("unroll") for (int k = 0; k < 2; ++k) dst[m][k] = *(const PG8_LAS bf16x8*)(lds + PG8_SA(b, h) + aoff + m * 2048 + k * 1024); } while (0)
; #define PG8_LDB(dst, b, h) do { _Pragma("unroll") for (int n = 0; n < 2; ++n) _Pragma("unroll") for (int k = 0; k < 2; ++k) dst[n][k] = *(const PG8_LAS bf16x8*)(lds + PG8_SB(b, h) + boff + n * 2048 + k * 1024); } while (0)
; #define PG8_MMA(ai, bj, At, Bt) do { __builtin_amdgcn_s_setprio(1); _Pragma("unroll") for (int m = 0; m < 4; ++m) _Pragma("unroll") for (int n = 0; n < 2; ++n) _Pragma("unroll") for (int k = 0; k < 2; ++k) \
;         acc[ai][bj][m][n] = __builtin_amdgcn_mfma_f32_16x16x32_bf16(Bt[n][k], At[m][k], acc[ai][bj][m][n], 0, 0, 0); __builtin_amdgcn_s_setprio(0); } while (0)
; #define PG8_WAIT_V(n) asm volatile("s_waitcnt vmcnt(" #n ")" ::: "memory")
; #define PG8_WAIT_L(n) asm volatile("s_waitcnt lgkmcnt(" #n ")" ::: "memory")
; #define PG8_BAR __builtin_amdgcn_s_barrier()
; #define PG8_SCHED __builtin_amdgcn_sched_barrier(0)
;     ...
;             PG8_WAIT_V(8); PG8_WAIT_L(0); PG8_BAR; PG8_MMA(1, 0, At, B0); PG8_MMA(1, 1, At, B1); PG8_BAR; PG8_SCHED;
;             PG8_LDB(B0, 1, 0); PG8_LDB(B1, 1, 1); PG8_SCHED; PG8_LDA(At, 1, 0); PG8_STAGE(PG8_SA(0, 1), a2 + hstepA, voffA);
;             PG8_WAIT_V(8); PG8_WAIT_L(0); PG8_BAR; PG8_MMA(0, 0, At, B0); PG8_MMA(0, 1, At, B1); PG8_BAR; PG8_SCHED;
;             PG8_LDA(At, 1, 1); PG8_STAGE(PG8_SB(1, 0), b3, voffB); PG8_STAGE(PG8_SB(1, 1), b3 + hstepB, voffB); PG8_STAGE(PG8_SA(1, 0), a3, voffA);
	s_setprio 1
	s_waitcnt lgkmcnt(0)
	v_mfma_f32_16x16x32_bf16 v[60:63], v[132:135], v[178:181], 0
	v_mfma_f32_16x16x32_bf16 v[56:59], v[140:143], v[178:181], 0
	v_mfma_f32_16x16x32_bf16 v[44:47], v[132:135], v[186:189], 0
	v_mfma_f32_16x16x32_bf16 v[40:43], v[140:143], v[186:189], 0
	v_mfma_f32_16x16x32_bf16 v[28:31], v[132:135], v[194:197], 0
	v_mfma_f32_16x16x32_bf16 v[24:27], v[140:143], v[194:197], 0
	v_mfma_f32_16x16x32_bf16 v[12:15], v[132:135], v[218:221], 0
	v_mfma_f32_16x16x32_bf16 v[8:11], v[140:143], v[218:221], 0
	v_mfma_f32_16x16x32_bf16 v[60:63], v[136:139], v[182:185], v[60:63]
	v_mfma_f32_16x16x32_bf16 v[56:59], v[144:147], v[182:185], v[56:59]
	v_mfma_f32_16x16x32_bf16 v[44:47], v[136:139], v[190:193], v[44:47]
	v_mfma_f32_16x16x32_bf16 v[40:43], v[144:147], v[190:193], v[40:43]
	v_mfma_f32_16x16x32_bf16 v[28:31], v[136:139], v[198:201], v[28:31]
	v_mfma_f32_16x16x32_bf16 v[24:27], v[144:147], v[198:201], v[24:27]
	v_mfma_f32_16x16x32_bf16 v[12:15], v[136:139], v[222:225], v[12:15]
	v_mfma_f32_16x16x32_bf16 v[8:11], v[144:147], v[222:225], v[8:11]
	s_setprio 0
	s_setprio 1
	v_mfma_f32_16x16x32_bf16 v[52:55], v[148:151], v[178:181], 0
	v_mfma_f32_16x16x32_bf16 v[48:51], v[170:173], v[178:181], 0
	v_mfma_f32_16x16x32_bf16 v[36:39], v[148:151], v[186:189], 0
	v_mfma_f32_16x16x32_bf16 v[32:35], v[170:173], v[186:189], 0
	v_mfma_f32_16x16x32_bf16 v[20:23], v[148:151], v[194:197], 0
	v_mfma_f32_16x16x32_bf16 v[16:19], v[170:173], v[194:197], 0
	v_mfma_f32_16x16x32_bf16 v[4:7], v[148:151], v[218:221], 0
	v_mfma_f32_16x16x32_bf16 v[0:3], v[170:173], v[218:221], 0
	v_mfma_f32_16x16x32_bf16 v[52:55], v[152:155], v[182:185], v[52:55]
	v_mfma_f32_16x16x32_bf16 v[48:51], v[174:177], v[182:185], v[48:51]
	v_mfma_f32_16x16x32_bf16 v[36:39], v[152:155], v[190:193], v[36:39]
	v_mfma_f32_16x16x32_bf16 v[32:35], v[174:177], v[190:193], v[32:35]
	v_mfma_f32_16x16x32_bf16 v[20:23], v[152:155], v[198:201], v[20:23]
	v_mfma_f32_16x16x32_bf16 v[16:19], v[174:177], v[198:201], v[16:19]
	v_mfma_f32_16x16x32_bf16 v[4:7], v[152:155], v[222:225], v[4:7]
	v_mfma_f32_16x16x32_bf16 v[0:3], v[174:177], v[222:225], v[0:3]
	s_setprio 0
	s_barrier
	s_add_i32 s68, 0, 0x18000
	s_add_i32 s69, 0, 0x1c000
	v_add_u32_e32 v144, s68, v203
	v_add_u32_e32 v174, s69, v203
	ds_read_b128 v[132:135], v144
	ds_read_b128 v[136:139], v144 offset:1024
	ds_read_b128 v[140:143], v144 offset:2048
	ds_read_b128 v[144:147], v144 offset:3072
	ds_read_b128 v[148:151], v174
	ds_read_b128 v[152:155], v174 offset:1024
	ds_read_b128 v[170:173], v174 offset:2048
	ds_read_b128 v[174:177], v174 offset:3072
	s_add_u32 s26, s26, 0x40000
	s_addc_u32 s27, s27, 0
	s_mov_b32 m0, s45
	v_lshl_add_u64 v[242:243], s[26:27], 0, v[160:161]
	ds_read_b128 v[178:181], v211 offset:32768
	ds_read_b128 v[182:185], v211 offset:33792
	ds_read_b128 v[186:189], v211 offset:34816
	ds_read_b128 v[190:193], v211 offset:35840
	ds_read_b128 v[194:197], v211 offset:36864
	ds_read_b128 v[198:201], v211 offset:37888
	ds_read_b128 v[218:221], v211 offset:38912
	ds_read_b128 v[222:225], v211 offset:39936
	global_load_lds_dwordx4 v[242:243], off
	v_lshl_add_u64 v[242:243], s[26:27], 0, v[158:159]
	s_mov_b32 m0, s46
	s_nop 0
	global_load_lds_dwordx4 v[242:243], off
	s_waitcnt vmcnt(8)
	s_waitcnt lgkmcnt(0)
	s_barrier
	s_setprio 1
	s_waitcnt lgkmcnt(0)
	v_mfma_f32_16x16x32_bf16 v[120:123], v[132:135], v[178:181], v[120:123]
	v_mfma_f32_16x16x32_bf16 v[116:119], v[140:143], v[178:181], v[116:119]
	v_mfma_f32_16x16x32_bf16 v[108:111], v[132:135], v[186:189], v[108:111]
	v_mfma_f32_16x16x32_bf16 v[104:107], v[140:143], v[186:189], v[104:107]
	v_mfma_f32_16x16x32_bf16 v[92:95], v[132:135], v[194:197], v[92:95]
	v_mfma_f32_16x16x32_bf16 v[88:91], v[140:143], v[194:197], v[88:91]
	v_mfma_f32_16x16x32_bf16 v[76:79], v[132:135], v[218:221], v[76:79]
	v_mfma_f32_16x16x32_bf16 v[72:75], v[140:143], v[218:221], v[72:75]
	v_mfma_f32_16x16x32_bf16 v[120:123], v[136:139], v[182:185], v[120:123]
	v_mfma_f32_16x16x32_bf16 v[116:119], v[144:147], v[182:185], v[116:119]
	v_mfma_f32_16x16x32_bf16 v[108:111], v[136:139], v[190:193], v[108:111]
	v_mfma_f32_16x16x32_bf16 v[104:107], v[144:147], v[190:193], v[104:107]
	v_mfma_f32_16x16x32_bf16 v[92:95], v[136:139], v[198:201], v[92:95]
	v_mfma_f32_16x16x32_bf16 v[88:91], v[144:147], v[198:201], v[88:91]
	v_mfma_f32_16x16x32_bf16 v[76:79], v[136:139], v[222:225], v[76:79]
	v_mfma_f32_16x16x32_bf16 v[72:75], v[144:147], v[222:225], v[72:75]
	s_setprio 0
	s_setprio 1
	v_mfma_f32_16x16x32_bf16 v[128:131], v[148:151], v[178:181], v[128:131]
	v_mfma_f32_16x16x32_bf16 v[124:127], v[170:173], v[178:181], v[124:127]
	v_mfma_f32_16x16x32_bf16 v[100:103], v[148:151], v[186:189], v[100:103]
	v_mfma_f32_16x16x32_bf16 v[96:99], v[170:173], v[186:189], v[96:99]
	v_mfma_f32_16x16x32_bf16 v[84:87], v[148:151], v[194:197], v[84:87]
	v_mfma_f32_16x16x32_bf16 v[80:83], v[170:173], v[194:197], v[80:83]
	v_mfma_f32_16x16x32_bf16 v[68:71], v[148:151], v[218:221], v[68:71]
	v_mfma_f32_16x16x32_bf16 v[64:67], v[170:173], v[218:221], v[64:67]
	v_mfma_f32_16x16x32_bf16 v[128:131], v[152:155], v[182:185], v[128:131]
	v_mfma_f32_16x16x32_bf16 v[124:127], v[174:177], v[182:185], v[124:127]
	v_mfma_f32_16x16x32_bf16 v[100:103], v[152:155], v[190:193], v[100:103]
	v_mfma_f32_16x16x32_bf16 v[96:99], v[174:177], v[190:193], v[96:99]
	v_mfma_f32_16x16x32_bf16 v[84:87], v[152:155], v[198:201], v[84:87]
	v_mfma_f32_16x16x32_bf16 v[80:83], v[174:177], v[198:201], v[80:83]
	v_mfma_f32_16x16x32_bf16 v[68:71], v[152:155], v[222:225], v[68:71]
	v_mfma_f32_16x16x32_bf16 v[64:67], v[174:177], v[222:225], v[64:67]
	s_setprio 0
	s_barrier
; #define PG8_STAGE(bufoff, gbase, voff) do { _Pragma("unroll") for (int _i = 0; _i < 2; ++_i) \
;         __builtin_amdgcn_global_load_lds((const unsigned*)((const char*)(gbase) + (voff)[_i]), (PG8_LAS unsigned*)(lds + (bufoff) + ldsw + _i * 8192), 16, 0, 0); } while (0)
; #define PG8_LDA(dst, b, h) do { _Pragma("unroll") for (int m = 0; m < 4; ++m) _Pragma("unroll") for (int k = 0; k < 2; ++k) dst[m][k] = *(const PG8_LAS bf16x8*)(lds + PG8_SA(b, h) + aoff + m * 2048 + k * 1024); } while (0)
; #define PG8_MMA(ai, bj, At, Bt) do { __builtin_amdgcn_s_setprio(1); _Pragma("unroll") for (int m = 0; m < 4; ++m) _Pragma("unroll") for (int n = 0; n < 2; ++n) _Pragma("unroll") for (int k = 0; k < 2; ++k) \
;         acc[ai][bj][m][n] = __builtin_amdgcn_mfma_f32_16x16x32_bf16(Bt[n][k], At[m][k], acc[ai][bj][m][n], 0, 0, 0); __builtin_amdgcn_s_setprio(0); } while (0)
; #define PG8_WAIT_V(n) asm volatile("s_waitcnt vmcnt(" #n ")" ::: "memory")
; #define PG8_WAIT_L(n) asm volatile("s_waitcnt lgkmcnt(" #n ")" ::: "memory")
; #define PG8_BAR __builtin_amdgcn_s_barrier()
; #define PG8_SCHED __builtin_amdgcn_sched_barrier(0)
;     ...
;         for (int t = 0; t < nt; t += 2) {
;     ...
;             PG8_LDA(At, 1, 1); PG8_STAGE(PG8_SB(1, 0), b3, voffB); PG8_STAGE(PG8_SB(1, 1), b3 + hstepB, voffB); PG8_STAGE(PG8_SA(1, 0), a3, voffA);
;             PG8_WAIT_V(8); PG8_WAIT_L(0); PG8_BAR; PG8_MMA(1, 0, At, B0); PG8_MMA(1, 1, At, B1); PG8_BAR; PG8_SCHED;
;         }
	s_add_i32 s26, s68, s31
	v_lshl_add_u64 v[238:239], v[238:239], 0, s[72:73]
	s_mov_b32 m0, s26
	ds_read_b128 v[178:181], v211 offset:49152
	ds_read_b128 v[182:185], v211 offset:50176
	ds_read_b128 v[186:189], v211 offset:51200
	ds_read_b128 v[190:193], v211 offset:52224
	ds_read_b128 v[194:197], v211 offset:53248
	ds_read_b128 v[198:201], v211 offset:54272
	ds_read_b128 v[218:221], v211 offset:55296
	ds_read_b128 v[222:225], v211 offset:56320
	global_load_lds_dwordx4 v[238:239], off
	s_add_i32 m0, s26, 0x2000
	s_add_u32 s24, s24, 0x40080
	v_lshl_add_u64 v[238:239], v[240:241], 0, s[72:73]
	s_addc_u32 s25, s25, 0
	s_add_i32 s26, s69, s31
	global_load_lds_dwordx4 v[238:239], off
	v_lshl_add_u64 v[238:239], s[24:25], 0, v[208:209]
	s_mov_b32 m0, s26
	s_nop 0
	global_load_lds_dwordx4 v[238:239], off
	v_lshl_add_u64 v[238:239], s[24:25], 0, v[156:157]
	s_add_i32 m0, s26, 0x2000
	s_nop 0
	global_load_lds_dwordx4 v[238:239], off
	v_lshl_add_u64 v[238:239], s[20:21], 0, v[160:161]
	s_mov_b32 m0, s47
	s_nop 0
	global_load_lds_dwordx4 v[238:239], off
	v_lshl_add_u64 v[238:239], s[20:21], 0, v[158:159]
	s_mov_b32 m0, s48
	s_nop 0
	global_load_lds_dwordx4 v[238:239], off
	s_waitcnt vmcnt(8)
	s_waitcnt lgkmcnt(0)
	s_barrier
	s_setprio 1
	s_waitcnt lgkmcnt(0)
	v_mfma_f32_16x16x32_bf16 v[60:63], v[132:135], v[178:181], v[60:63]
	v_mfma_f32_16x16x32_bf16 v[56:59], v[140:143], v[178:181], v[56:59]
	v_mfma_f32_16x16x32_bf16 v[44:47], v[132:135], v[186:189], v[44:47]
	v_mfma_f32_16x16x32_bf16 v[40:43], v[140:143], v[186:189], v[40:43]
	v_mfma_f32_16x16x32_bf16 v[28:31], v[132:135], v[194:197], v[28:31]
	v_mfma_f32_16x16x32_bf16 v[24:27], v[140:143], v[194:197], v[24:27]
	v_mfma_f32_16x16x32_bf16 v[12:15], v[132:135], v[218:221], v[12:15]
	v_mfma_f32_16x16x32_bf16 v[8:11], v[140:143], v[218:221], v[8:11]
	v_mfma_f32_16x16x32_bf16 v[60:63], v[136:139], v[182:185], v[60:63]
	v_mfma_f32_16x16x32_bf16 v[56:59], v[144:147], v[182:185], v[56:59]
	v_mfma_f32_16x16x32_bf16 v[44:47], v[136:139], v[190:193], v[44:47]
	v_mfma_f32_16x16x32_bf16 v[40:43], v[144:147], v[190:193], v[40:43]
	v_mfma_f32_16x16x32_bf16 v[28:31], v[136:139], v[198:201], v[28:31]
	v_mfma_f32_16x16x32_bf16 v[24:27], v[144:147], v[198:201], v[24:27]
	v_mfma_f32_16x16x32_bf16 v[12:15], v[136:139], v[222:225], v[12:15]
	v_mfma_f32_16x16x32_bf16 v[8:11], v[144:147], v[222:225], v[8:11]
	s_setprio 0
	s_setprio 1
	v_mfma_f32_16x16x32_bf16 v[52:55], v[148:151], v[178:181], v[52:55]
	v_mfma_f32_16x16x32_bf16 v[48:51], v[170:173], v[178:181], v[48:51]
	v_mfma_f32_16x16x32_bf16 v[36:39], v[148:151], v[186:189], v[36:39]
	v_mfma_f32_16x16x32_bf16 v[32:35], v[170:173], v[186:189], v[32:35]
	v_mfma_f32_16x16x32_bf16 v[20:23], v[148:151], v[194:197], v[20:23]
	v_mfma_f32_16x16x32_bf16 v[16:19], v[170:173], v[194:197], v[16:19]
	v_mfma_f32_16x16x32_bf16 v[4:7], v[148:151], v[218:221], v[4:7]
	v_mfma_f32_16x16x32_bf16 v[0:3], v[170:173], v[218:221], v[0:3]
	v_mfma_f32_16x16x32_bf16 v[52:55], v[152:155], v[182:185], v[52:55]
	v_mfma_f32_16x16x32_bf16 v[48:51], v[174:177], v[182:185], v[48:51]
	v_mfma_f32_16x16x32_bf16 v[36:39], v[152:155], v[190:193], v[36:39]
	v_mfma_f32_16x16x32_bf16 v[32:35], v[174:177], v[190:193], v[32:35]
	v_mfma_f32_16x16x32_bf16 v[20:23], v[152:155], v[198:201], v[20:23]
	v_mfma_f32_16x16x32_bf16 v[16:19], v[174:177], v[198:201], v[16:19]
	v_mfma_f32_16x16x32_bf16 v[4:7], v[152:155], v[222:225], v[4:7]
	v_mfma_f32_16x16x32_bf16 v[0:3], v[174:177], v[222:225], v[0:3]
	s_setprio 0
	s_barrier
	s_add_i32 s67, s67, 2
	s_add_u32 s18, s18, 0x100
	s_addc_u32 s19, s19, 0
	s_cmp_gt_u32 s67, 13
	s_cbranch_scc0 .LBB0_451
	s_branch .Lpeel_exit_451
	.p2alignl 6, 3212836864

;     __device__ __forceinline__ const char* tile(const Unit& u, int t) const { return A + (size_t)u.pm * 2 * hstep() + (size_t)t * (BK * 2); }
;     __device__ __forceinline__ const char* tile(const Unit& u, int t) const { return U + (long)(t >> 2) * xoff + (size_t)u.pn * (1024 * 512) + (size_t)u.pm * 2 * hstep() + (size_t)(t & 3) * (BK * 2); }
; #define PG8_STAGE(bufoff, gbase, voff) do { _Pragma("unroll") for (int _i = 0; _i < 2; ++_i) \
;         __builtin_amdgcn_global_load_lds((const unsigned*)((const char*)(gbase) + (voff)[_i]), (PG8_LAS unsigned*)(lds + (bufoff) + ldsw + _i * 8192), 16, 0, 0); } while (0)
; #define PG8_LDA(dst, b, h) do { _Pragma("unroll") for (int m = 0; m < 4; ++m) _Pragma("unroll") for (int k = 0; k < 2; ++k) dst[m][k] = *(const PG8_LAS bf16x8*)(lds + PG8_SA(b, h) + aoff + m * 2048 + k * 1024); } while (0)
; #define PG8_LDB(dst, b, h) do { _Pragma("unroll") for (int n = 0; n < 2; ++n) _Pragma("unroll") for (int k = 0; k < 2; ++k) dst[n][k] = *(const PG8_LAS bf16x8*)(lds + PG8_SB(b, h) + boff + n * 2048 + k * 1024); } while (0)
; #define PG8_MMA(ai, bj, At, Bt) do { __builtin_amdgcn_s_setprio(1); _Pragma("unroll") for (int m = 0; m < 4; ++m) _Pragma("unroll") for (int n = 0; n < 2; ++n) _Pragma("unroll") for (int k = 0; k < 2; ++k) \
;         acc[ai][bj][m][n] = __builtin_amdgcn_mfma_f32_16x16x32_bf16(Bt[n][k], At[m][k], acc[ai][bj][m][n], 0, 0, 0); __builtin_amdgcn_s_setprio(0); } while (0)
; #define PG8_WAIT_V(n) asm volatile("s_waitcnt vmcnt(" #n ")" ::: "memory")
;     ...
;             const bool last = (t == nt - 2);
;             const char* a1 = AS.tile(cur, t + 1);
;             const char* a2 = last ? AS.tile(nu, 0) : AS.tile(cur, t + 2); const char* b2 = last ? nB : cB + (size_t)(t + 2) * kstep;
;             const char* a3 = last ? AS.tile(nu, 1) : AS.tile(cur, t + 3); const char* b3 = b2 + kstep;
;             PG8_LDB(B0, 0, 0); PG8_LDB(B1, 0, 1); PG8_SCHED; PG8_LDA(At, 0, 0); PG8_STAGE(PG8_SA(1, 1), a1 + hstepA, voffA);
;             PG8_WAIT_V(8); PG8_WAIT_L(0); PG8_BAR; PG8_MMA(0, 0, At, B0); PG8_MMA(0, 1, At, B1); PG8_BAR; PG8_SCHED;
;             PG8_LDA(At, 0, 1); PG8_STAGE(PG8_SB(0, 0), b2, voffB); PG8_STAGE(PG8_SB(0, 1), b2 + hstepB, voffB); PG8_STAGE(PG8_SA(0, 0), a2, voffA);
;             PG8_WAIT_V(8); PG8_WAIT_L(0); PG8_BAR; PG8_MMA(1, 0, At, B0); PG8_MMA(1, 1, At, B1); PG8_BAR; PG8_SCHED;
.Lpeel_504:
	s_add_u32 s14, s52, s12
	s_addc_u32 s15, s53, s13
	s_add_u32 s18, s14, 0x400100
	s_addc_u32 s19, s15, 0
	s_add_u32 s16, s54, s12
	s_addc_u32 s17, s55, s13
	s_add_u32 s14, s14, 0x400180
	s_addc_u32 s15, s15, 0
	s_add_i32 s57, 0, 0x10000
	s_add_i32 s60, 0, 0x14000
	v_add_u32_e32 v146, s57, v149
	ds_read_b128 v[156:159], v146
	ds_read_b128 v[160:163], v146 offset:1024
	ds_read_b128 v[164:167], v146 offset:2048
	ds_read_b128 v[168:171], v146 offset:3072
	v_add_u32_e32 v146, s60, v149
	ds_read_b128 v[172:175], v146
	ds_read_b128 v[176:179], v146 offset:1024
	ds_read_b128 v[180:183], v146 offset:2048
	ds_read_b128 v[184:187], v146 offset:3072
	s_cmpk_eq_i32 s12, 0x700
	s_cselect_b32 s15, s51, s15
	s_cselect_b32 s14, s50, s14
	s_cselect_b32 s17, s48, s17
	s_cselect_b32 s16, s47, s16
	s_cselect_b32 s19, s49, s19
	s_cselect_b32 s18, s11, s18
	v_lshl_add_u64 v[146:147], v[142:143], 0, s[12:13]
	s_add_i32 m0, s26, 0xc000
	ds_read_b128 v[188:191], v152
	ds_read_b128 v[192:195], v152 offset:1024
	ds_read_b128 v[196:199], v152 offset:2048
	ds_read_b128 v[200:203], v152 offset:3072
	ds_read_b128 v[204:207], v152 offset:4096
	ds_read_b128 v[218:221], v152 offset:5120
	ds_read_b128 v[222:225], v152 offset:6144
	ds_read_b128 v[238:241], v152 offset:7168
	global_load_lds_dwordx4 v[146:147], off
	v_lshl_add_u64 v[146:147], v[144:145], 0, s[12:13]
	s_add_i32 m0, s26, 0xe000
	s_nop 0
	global_load_lds_dwordx4 v[146:147], off
	s_waitcnt vmcnt(24)
	s_waitcnt lgkmcnt(0)
	s_barrier
	s_setprio 1
	s_waitcnt lgkmcnt(0)
	v_mfma_f32_16x16x32_bf16 v[124:127], v[156:159], v[188:191], 0
	v_mfma_f32_16x16x32_bf16 v[120:123], v[164:167], v[188:191], 0
	v_mfma_f32_16x16x32_bf16 v[108:111], v[156:159], v[196:199], 0
	v_mfma_f32_16x16x32_bf16 v[104:107], v[164:167], v[196:199], 0
	v_mfma_f32_16x16x32_bf16 v[92:95], v[156:159], v[204:207], 0
	v_mfma_f32_16x16x32_bf16 v[88:91], v[164:167], v[204:207], 0
	v_mfma_f32_16x16x32_bf16 v[76:79], v[156:159], v[222:225], 0
	v_mfma_f32_16x16x32_bf16 v[72:75], v[164:167], v[222:225], 0
	v_mfma_f32_16x16x32_bf16 v[124:127], v[160:163], v[192:195], v[124:127]
	v_mfma_f32_16x16x32_bf16 v[120:123], v[168:171], v[192:195], v[120:123]
	v_mfma_f32_16x16x32_bf16 v[108:111], v[160:163], v[200:203], v[108:111]
	v_mfma_f32_16x16x32_bf16 v[104:107], v[168:171], v[200:203], v[104:107]
	v_mfma_f32_16x16x32_bf16 v[92:95], v[160:163], v[218:221], v[92:95]
	v_mfma_f32_16x16x32_bf16 v[88:91], v[168:171], v[218:221], v[88:91]
	v_mfma_f32_16x16x32_bf16 v[76:79], v[160:163], v[238:241], v[76:79]
	v_mfma_f32_16x16x32_bf16 v[72:75], v[168:171], v[238:241], v[72:75]
	s_setprio 0
	s_setprio 1
	v_mfma_f32_16x16x32_bf16 v[116:119], v[172:175], v[188:191], 0
	v_mfma_f32_16x16x32_bf16 v[112:115], v[180:183], v[188:191], 0
	v_mfma_f32_16x16x32_bf16 v[100:103], v[172:175], v[196:199], 0
	v_mfma_f32_16x16x32_bf16 v[96:99], v[180:183], v[196:199], 0
	v_mfma_f32_16x16x32_bf16 v[84:87], v[172:175], v[204:207], 0
	v_mfma_f32_16x16x32_bf16 v[80:83], v[180:183], v[204:207], 0
	v_mfma_f32_16x16x32_bf16 v[68:71], v[172:175], v[222:225], 0
	v_mfma_f32_16x16x32_bf16 v[64:67], v[180:183], v[222:225], 0
	v_mfma_f32_16x16x32_bf16 v[116:119], v[176:179], v[192:195], v[116:119]
	v_mfma_f32_16x16x32_bf16 v[112:115], v[184:187], v[192:195], v[112:115]
	v_mfma_f32_16x16x32_bf16 v[100:103], v[176:179], v[200:203], v[100:103]
	v_mfma_f32_16x16x32_bf16 v[96:99], v[184:187], v[200:203], v[96:99]
	v_mfma_f32_16x16x32_bf16 v[84:87], v[176:179], v[218:221], v[84:87]
	v_mfma_f32_16x16x32_bf16 v[80:83], v[184:187], v[218:221], v[80:83]
	v_mfma_f32_16x16x32_bf16 v[68:71], v[176:179], v[238:241], v[68:71]
	v_mfma_f32_16x16x32_bf16 v[64:67], v[184:187], v[238:241], v[64:67]
	s_setprio 0
	s_barrier
	s_add_i32 s57, s57, s25
	v_lshl_add_u64 v[146:147], s[16:17], 0, v[208:209]
	s_mov_b32 m0, s57
	ds_read_b128 v[188:191], v152 offset:16384
	ds_read_b128 v[192:195], v152 offset:17408
	ds_read_b128 v[196:199], v152 offset:18432
	ds_read_b128 v[200:203], v152 offset:19456
	ds_read_b128 v[204:207], v152 offset:20480
	ds_read_b128 v[218:221], v152 offset:21504
	ds_read_b128 v[222:225], v152 offset:22528
	ds_read_b128 v[238:241], v152 offset:23552
	global_load_lds_dwordx4 v[146:147], off
	s_add_i32 m0, s57, 0x2000
	s_add_u32 s58, s16, 0x40000
	v_lshl_add_u64 v[242:243], s[16:17], 0, v[128:129]
	s_addc_u32 s59, s17, 0
	s_add_i32 s57, s60, s25
	global_load_lds_dwordx4 v[242:243], off
	v_lshl_add_u64 v[244:245], s[58:59], 0, v[208:209]
	s_mov_b32 m0, s57
	s_nop 0
	global_load_lds_dwordx4 v[244:245], off
	v_lshl_add_u64 v[244:245], s[58:59], 0, v[128:129]
	s_add_i32 m0, s57, 0x2000
	s_nop 0
	global_load_lds_dwordx4 v[244:245], off
	v_lshl_add_u64 v[244:245], s[18:19], 0, v[132:133]
	s_mov_b32 m0, s26
	s_nop 0
	global_load_lds_dwordx4 v[244:245], off
	v_lshl_add_u64 v[244:245], s[18:19], 0, v[130:131]
	s_mov_b32 m0, s27
	s_nop 0
	global_load_lds_dwordx4 v[244:245], off
	s_waitcnt vmcnt(8)
	s_waitcnt lgkmcnt(0)
	s_barrier
; #define PG8_STAGE(bufoff, gbase, voff) do { _Pragma("unroll") for (int _i = 0; _i < 2; ++_i) \
;         __builtin_amdgcn_global_load_lds((const unsigned*)((const char*)(gbase) + (voff)[_i]), (PG8_LAS unsigned*)(lds + (bufoff) + ldsw + _i * 8192), 16, 0, 0); } while (0)
; #define PG8_LDA(dst, b, h) do { _Pragma("unroll") for (int m = 0; m < 4; ++m) _Pragma("unroll") for (int k = 0; k < 2; ++k) dst[m][k] = *(const PG8_LAS bf16x8*)(lds + PG8_SA(b, h) + aoff + m * 2048 + k * 1024); } while (0)
; #define PG8_LDB(dst, b, h) do { _Pragma("unroll") for (int n = 0; n < 2; ++n) _Pragma("unroll") for (int k = 0; k < 2; ++k) dst[n][k] = *(const PG8_LAS bf16x8*)(lds + PG8_SB(b, h) + boff + n * 2048 + k * 1024); } while (0)
; #define PG8_MMA(ai, bj, At, Bt) do { __builtin_amdgcn_s_setprio(1); _Pragma("unroll") for (int m = 0; m < 4; ++m) _Pragma("unroll") for (int n = 0; n < 2; ++n) _Pragma("unroll") for (int k = 0; k < 2; ++k) \
;         acc[ai][bj][m][n] = __builtin_amdgcn_mfma_f32_16x16x32_bf16(Bt[n][k], At[m][k], acc[ai][bj][m][n], 0, 0, 0); __builtin_amdgcn_s_setprio(0); } while (0)
; #define PG8_WAIT_V(n) asm volatile("s_waitcnt vmcnt(" #n ")" ::: "memory")
; #define PG8_WAIT_L(n) asm volatile("s_waitcnt lgkmcnt(" #n ")" ::: "memory")
; #define PG8_BAR __builtin_amdgcn_s_barrier()
; #define PG8_SCHED __builtin_amdgcn_sched_barrier(0)
;     ...
;             PG8_WAIT_V(8); PG8_WAIT_L(0); PG8_BAR; PG8_MMA(1, 0, At, B0); PG8_MMA(1, 1, At, B1); PG8_BAR; PG8_SCHED;
;             PG8_LDB(B0, 1, 0); PG8_LDB(B1, 1, 1); PG8_SCHED; PG8_LDA(At, 1, 0); PG8_STAGE(PG8_SA(0, 1), a2 + hstepA, voffA);
;             PG8_WAIT_V(8); PG8_WAIT_L(0); PG8_BAR; PG8_MMA(0, 0, At, B0); PG8_MMA(0, 1, At, B1); PG8_BAR; PG8_SCHED;
	s_setprio 1
	s_waitcnt lgkmcnt(0)
	v_mfma_f32_16x16x32_bf16 v[60:63], v[156:159], v[188:191], 0
	v_mfma_f32_16x16x32_bf16 v[56:59], v[164:167], v[188:191], 0
	v_mfma_f32_16x16x32_bf16 v[44:47], v[156:159], v[196:199], 0
	v_mfma_f32_16x16x32_bf16 v[40:43], v[164:167], v[196:199], 0
	v_mfma_f32_16x16x32_bf16 v[28:31], v[156:159], v[204:207], 0
	v_mfma_f32_16x16x32_bf16 v[24:27], v[164:167], v[204:207], 0
	v_mfma_f32_16x16x32_bf16 v[12:15], v[156:159], v[222:225], 0
	v_mfma_f32_16x16x32_bf16 v[8:11], v[164:167], v[222:225], 0
	v_mfma_f32_16x16x32_bf16 v[60:63], v[160:163], v[192:195], v[60:63]
	v_mfma_f32_16x16x32_bf16 v[56:59], v[168:171], v[192:195], v[56:59]
	v_mfma_f32_16x16x32_bf16 v[44:47], v[160:163], v[200:203], v[44:47]
	v_mfma_f32_16x16x32_bf16 v[40:43], v[168:171], v[200:203], v[40:43]
	v_mfma_f32_16x16x32_bf16 v[28:31], v[160:163], v[218:221], v[28:31]
	v_mfma_f32_16x16x32_bf16 v[24:27], v[168:171], v[218:221], v[24:27]
	v_mfma_f32_16x16x32_bf16 v[12:15], v[160:163], v[238:241], v[12:15]
	v_mfma_f32_16x16x32_bf16 v[8:11], v[168:171], v[238:241], v[8:11]
	s_setprio 0
	s_setprio 1
	v_mfma_f32_16x16x32_bf16 v[52:55], v[172:175], v[188:191], 0
	v_mfma_f32_16x16x32_bf16 v[48:51], v[180:183], v[188:191], 0
	v_mfma_f32_16x16x32_bf16 v[36:39], v[172:175], v[196:199], 0
	v_mfma_f32_16x16x32_bf16 v[32:35], v[180:183], v[196:199], 0
	v_mfma_f32_16x16x32_bf16 v[20:23], v[172:175], v[204:207], 0
	v_mfma_f32_16x16x32_bf16 v[16:19], v[180:183], v[204:207], 0
	v_mfma_f32_16x16x32_bf16 v[4:7], v[172:175], v[222:225], 0
	v_mfma_f32_16x16x32_bf16 v[0:3], v[180:183], v[222:225], 0
	v_mfma_f32_16x16x32_bf16 v[52:55], v[176:179], v[192:195], v[52:55]
	v_mfma_f32_16x16x32_bf16 v[48:51], v[184:187], v[192:195], v[48:51]
	v_mfma_f32_16x16x32_bf16 v[36:39], v[176:179], v[200:203], v[36:39]
	v_mfma_f32_16x16x32_bf16 v[32:35], v[184:187], v[200:203], v[32:35]
	v_mfma_f32_16x16x32_bf16 v[20:23], v[176:179], v[218:221], v[20:23]
	v_mfma_f32_16x16x32_bf16 v[16:19], v[184:187], v[218:221], v[16:19]
	v_mfma_f32_16x16x32_bf16 v[4:7], v[176:179], v[238:241], v[4:7]
	v_mfma_f32_16x16x32_bf16 v[0:3], v[184:187], v[238:241], v[0:3]
	s_setprio 0
	s_barrier
	s_add_i32 s57, 0, 0x18000
	v_add_u32_e32 v155, s57, v149
	s_add_i32 s58, 0, 0x1c000
	ds_read_b128 v[156:159], v155
	ds_read_b128 v[160:163], v155 offset:1024
	ds_read_b128 v[164:167], v155 offset:2048
	ds_read_b128 v[168:171], v155 offset:3072
	v_add_u32_e32 v155, s58, v149
	ds_read_b128 v[172:175], v155
	ds_read_b128 v[176:179], v155 offset:1024
	ds_read_b128 v[180:183], v155 offset:2048
	ds_read_b128 v[184:187], v155 offset:3072
	s_add_u32 s18, s18, 0x40000
	s_addc_u32 s19, s19, 0
	s_mov_b32 m0, s28
	v_lshl_add_u64 v[244:245], s[18:19], 0, v[132:133]
	ds_read_b128 v[188:191], v152 offset:32768
	ds_read_b128 v[192:195], v152 offset:33792
	ds_read_b128 v[196:199], v152 offset:34816
	ds_read_b128 v[200:203], v152 offset:35840
	ds_read_b128 v[204:207], v152 offset:36864
	ds_read_b128 v[218:221], v152 offset:37888
	ds_read_b128 v[222:225], v152 offset:38912
	ds_read_b128 v[238:241], v152 offset:39936
	global_load_lds_dwordx4 v[244:245], off
	v_lshl_add_u64 v[244:245], s[18:19], 0, v[130:131]
	s_mov_b32 m0, s29
	s_nop 0
	global_load_lds_dwordx4 v[244:245], off
	s_waitcnt vmcnt(8)
	s_waitcnt lgkmcnt(0)
	s_barrier
	s_setprio 1
	s_waitcnt lgkmcnt(0)
	v_mfma_f32_16x16x32_bf16 v[124:127], v[156:159], v[188:191], v[124:127]
	v_mfma_f32_16x16x32_bf16 v[120:123], v[164:167], v[188:191], v[120:123]
	v_mfma_f32_16x16x32_bf16 v[108:111], v[156:159], v[196:199], v[108:111]
	v_mfma_f32_16x16x32_bf16 v[104:107], v[164:167], v[196:199], v[104:107]
	v_mfma_f32_16x16x32_bf16 v[92:95], v[156:159], v[204:207], v[92:95]
	v_mfma_f32_16x16x32_bf16 v[88:91], v[164:167], v[204:207], v[88:91]
	v_mfma_f32_16x16x32_bf16 v[76:79], v[156:159], v[222:225], v[76:79]
	v_mfma_f32_16x16x32_bf16 v[72:75], v[164:167], v[222:225], v[72:75]
	v_mfma_f32_16x16x32_bf16 v[124:127], v[160:163], v[192:195], v[124:127]
	v_mfma_f32_16x16x32_bf16 v[120:123], v[168:171], v[192:195], v[120:123]
	v_mfma_f32_16x16x32_bf16 v[108:111], v[160:163], v[200:203], v[108:111]
	v_mfma_f32_16x16x32_bf16 v[104:107], v[168:171], v[200:203], v[104:107]
	v_mfma_f32_16x16x32_bf16 v[92:95], v[160:163], v[218:221], v[92:95]
	v_mfma_f32_16x16x32_bf16 v[88:91], v[168:171], v[218:221], v[88:91]
	v_mfma_f32_16x16x32_bf16 v[76:79], v[160:163], v[238:241], v[76:79]
	v_mfma_f32_16x16x32_bf16 v[72:75], v[168:171], v[238:241], v[72:75]
	s_setprio 0
	s_setprio 1
	v_mfma_f32_16x16x32_bf16 v[116:119], v[172:175], v[188:191], v[116:119]
	v_mfma_f32_16x16x32_bf16 v[112:115], v[180:183], v[188:191], v[112:115]
	v_mfma_f32_16x16x32_bf16 v[100:103], v[172:175], v[196:199], v[100:103]
	v_mfma_f32_16x16x32_bf16 v[96:99], v[180:183], v[196:199], v[96:99]
	v_mfma_f32_16x16x32_bf16 v[84:87], v[172:175], v[204:207], v[84:87]
	v_mfma_f32_16x16x32_bf16 v[80:83], v[180:183], v[204:207], v[80:83]
	v_mfma_f32_16x16x32_bf16 v[68:71], v[172:175], v[222:225], v[68:71]
	v_mfma_f32_16x16x32_bf16 v[64:67], v[180:183], v[222:225], v[64:67]
	v_mfma_f32_16x16x32_bf16 v[116:119], v[176:179], v[192:195], v[116:119]
	v_mfma_f32_16x16x32_bf16 v[112:115], v[184:187], v[192:195], v[112:115]
	v_mfma_f32_16x16x32_bf16 v[100:103], v[176:179], v[200:203], v[100:103]
	v_mfma_f32_16x16x32_bf16 v[96:99], v[184:187], v[200:203], v[96:99]
	v_mfma_f32_16x16x32_bf16 v[84:87], v[176:179], v[218:221], v[84:87]
	v_mfma_f32_16x16x32_bf16 v[80:83], v[184:187], v[218:221], v[80:83]
	v_mfma_f32_16x16x32_bf16 v[68:71], v[176:179], v[238:241], v[68:71]
	v_mfma_f32_16x16x32_bf16 v[64:67], v[184:187], v[238:241], v[64:67]
	s_setprio 0
	s_barrier
; #define PG8_STAGE(bufoff, gbase, voff) do { _Pragma("unroll") for (int _i = 0; _i < 2; ++_i) \
;         __builtin_amdgcn_global_load_lds((const unsigned*)((const char*)(gbase) + (voff)[_i]), (PG8_LAS unsigned*)(lds + (bufoff) + ldsw + _i * 8192), 16, 0, 0); } while (0)
; #define PG8_LDA(dst, b, h) do { _Pragma("unroll") for (int m = 0; m < 4; ++m) _Pragma("unroll") for (int k = 0; k < 2; ++k) dst[m][k] = *(const PG8_LAS bf16x8*)(lds + PG8_SA(b, h) + aoff + m * 2048 + k * 1024); } while (0)
; #define PG8_MMA(ai, bj, At, Bt) do { __builtin_amdgcn_s_setprio(1); _Pragma("unroll") for (int m = 0; m < 4; ++m) _Pragma("unroll") for (int n = 0; n < 2; ++n) _Pragma("unroll") for (int k = 0; k < 2; ++k) \
;         acc[ai][bj][m][n] = __builtin_amdgcn_mfma_f32_16x16x32_bf16(Bt[n][k], At[m][k], acc[ai][bj][m][n], 0, 0, 0); __builtin_amdgcn_s_setprio(0); } while (0)
; #define PG8_WAIT_V(n) asm volatile("s_waitcnt vmcnt(" #n ")" ::: "memory")
; #define PG8_WAIT_L(n) asm volatile("s_waitcnt lgkmcnt(" #n ")" ::: "memory")
; #define PG8_BAR __builtin_amdgcn_s_barrier()
; #define PG8_SCHED __builtin_amdgcn_sched_barrier(0)
;     ...
;         for (int t = 0; t < nt; t += 2) {
;     ...
;             PG8_LDA(At, 1, 1); PG8_STAGE(PG8_SB(1, 0), b3, voffB); PG8_STAGE(PG8_SB(1, 1), b3 + hstepB, voffB); PG8_STAGE(PG8_SA(1, 0), a3, voffA);
;             PG8_WAIT_V(8); PG8_WAIT_L(0); PG8_BAR; PG8_MMA(1, 0, At, B0); PG8_MMA(1, 1, At, B1); PG8_BAR; PG8_SCHED;
	s_add_i32 s18, s57, s25
	v_lshl_add_u64 v[146:147], v[146:147], 0, s[64:65]
	s_mov_b32 m0, s18
	ds_read_b128 v[188:191], v152 offset:49152
	ds_read_b128 v[192:195], v152 offset:50176
	ds_read_b128 v[196:199], v152 offset:51200
	ds_read_b128 v[200:203], v152 offset:52224
	ds_read_b128 v[204:207], v152 offset:53248
	ds_read_b128 v[218:221], v152 offset:54272
	ds_read_b128 v[222:225], v152 offset:55296
	ds_read_b128 v[238:241], v152 offset:56320
	global_load_lds_dwordx4 v[146:147], off
	s_add_i32 m0, s18, 0x2000
	s_add_u32 s16, s16, 0x40080
	v_lshl_add_u64 v[146:147], v[242:243], 0, s[64:65]
	s_addc_u32 s17, s17, 0
	s_add_i32 s18, s58, s25
	global_load_lds_dwordx4 v[146:147], off
	v_lshl_add_u64 v[146:147], s[16:17], 0, v[208:209]
	s_mov_b32 m0, s18
	s_nop 0
	global_load_lds_dwordx4 v[146:147], off
	v_lshl_add_u64 v[146:147], s[16:17], 0, v[128:129]
	s_add_i32 m0, s18, 0x2000
	s_nop 0
	global_load_lds_dwordx4 v[146:147], off
	v_lshl_add_u64 v[146:147], s[14:15], 0, v[132:133]
	s_mov_b32 m0, s30
	s_nop 0
	global_load_lds_dwordx4 v[146:147], off
	v_lshl_add_u64 v[146:147], s[14:15], 0, v[130:131]
	s_mov_b32 m0, s31
	s_nop 0
	global_load_lds_dwordx4 v[146:147], off
	s_waitcnt vmcnt(8)
	s_waitcnt lgkmcnt(0)
	s_barrier
	s_setprio 1
	s_waitcnt lgkmcnt(0)
	v_mfma_f32_16x16x32_bf16 v[60:63], v[156:159], v[188:191], v[60:63]
	v_mfma_f32_16x16x32_bf16 v[56:59], v[164:167], v[188:191], v[56:59]
	v_mfma_f32_16x16x32_bf16 v[44:47], v[156:159], v[196:199], v[44:47]
	v_mfma_f32_16x16x32_bf16 v[40:43], v[164:167], v[196:199], v[40:43]
	v_mfma_f32_16x16x32_bf16 v[28:31], v[156:159], v[204:207], v[28:31]
	v_mfma_f32_16x16x32_bf16 v[24:27], v[164:167], v[204:207], v[24:27]
	v_mfma_f32_16x16x32_bf16 v[12:15], v[156:159], v[222:225], v[12:15]
	v_mfma_f32_16x16x32_bf16 v[8:11], v[164:167], v[222:225], v[8:11]
	v_mfma_f32_16x16x32_bf16 v[60:63], v[160:163], v[192:195], v[60:63]
	v_mfma_f32_16x16x32_bf16 v[56:59], v[168:171], v[192:195], v[56:59]
	v_mfma_f32_16x16x32_bf16 v[44:47], v[160:163], v[200:203], v[44:47]
	v_mfma_f32_16x16x32_bf16 v[40:43], v[168:171], v[200:203], v[40:43]
	v_mfma_f32_16x16x32_bf16 v[28:31], v[160:163], v[218:221], v[28:31]
	v_mfma_f32_16x16x32_bf16 v[24:27], v[168:171], v[218:221], v[24:27]
	v_mfma_f32_16x16x32_bf16 v[12:15], v[160:163], v[238:241], v[12:15]
	v_mfma_f32_16x16x32_bf16 v[8:11], v[168:171], v[238:241], v[8:11]
	s_setprio 0
	s_setprio 1
	v_mfma_f32_16x16x32_bf16 v[52:55], v[172:175], v[188:191], v[52:55]
	v_mfma_f32_16x16x32_bf16 v[48:51], v[180:183], v[188:191], v[48:51]
	v_mfma_f32_16x16x32_bf16 v[36:39], v[172:175], v[196:199], v[36:39]
	v_mfma_f32_16x16x32_bf16 v[32:35], v[180:183], v[196:199], v[32:35]
	v_mfma_f32_16x16x32_bf16 v[20:23], v[172:175], v[204:207], v[20:23]
	v_mfma_f32_16x16x32_bf16 v[16:19], v[180:183], v[204:207], v[16:19]
	v_mfma_f32_16x16x32_bf16 v[4:7], v[172:175], v[222:225], v[4:7]
	v_mfma_f32_16x16x32_bf16 v[0:3], v[180:183], v[222:225], v[0:3]
	v_mfma_f32_16x16x32_bf16 v[52:55], v[176:179], v[192:195], v[52:55]
	v_mfma_f32_16x16x32_bf16 v[48:51], v[184:187], v[192:195], v[48:51]
	v_mfma_f32_16x16x32_bf16 v[36:39], v[176:179], v[200:203], v[36:39]
	v_mfma_f32_16x16x32_bf16 v[32:35], v[184:187], v[200:203], v[32:35]
	v_mfma_f32_16x16x32_bf16 v[20:23], v[176:179], v[218:221], v[20:23]
	v_mfma_f32_16x16x32_bf16 v[16:19], v[184:187], v[218:221], v[16:19]
	v_mfma_f32_16x16x32_bf16 v[4:7], v[176:179], v[238:241], v[4:7]
	v_mfma_f32_16x16x32_bf16 v[0:3], v[184:187], v[238:241], v[0:3]
	s_setprio 0
	s_barrier
	s_add_i32 s56, s56, 2
	s_add_u32 s12, s12, 0x100
	s_addc_u32 s13, s13, 0
	s_cmp_gt_u32 s56, 13
	s_cbranch_scc0 .LBB0_504
	s_branch .Lpeel_exit_504
	.p2alignl 6, 3212836864

;     __device__ __forceinline__ const char* tile(const Unit& u, int t) const { return A + (size_t)u.pm * 2 * hstep() + (size_t)t * (BK * 2); }
;     __device__ __forceinline__ const char* tile(const Unit& u, int t) const { return U + (long)(t >> 2) * xoff + (size_t)u.pn * (1024 * 512) + (size_t)u.pm * 2 * hstep() + (size_t)(t & 3) * (BK * 2); }
; #define PG8_STAGE(bufoff, gbase, voff) do { _Pragma("unroll") for (int _i = 0; _i < 2; ++_i) \
;         __builtin_amdgcn_global_load_lds((const unsigned*)((const char*)(gbase) + (voff)[_i]), (PG8_LAS unsigned*)(lds + (bufoff) + ldsw + _i * 8192), 16, 0, 0); } while (0)
; #define PG8_LDA(dst, b, h) do { _Pragma("unroll") for (int m = 0; m < 4; ++m) _Pragma("unroll") for (int k = 0; k < 2; ++k) dst[m][k] = *(const PG8_LAS bf16x8*)(lds + PG8_SA(b, h) + aoff + m * 2048 + k * 1024); } while (0)
; #define PG8_LDB(dst, b, h) do { _Pragma("unroll") for (int n = 0; n < 2; ++n) _Pragma("unroll") for (int k = 0; k < 2; ++k) dst[n][k] = *(const PG8_LAS bf16x8*)(lds + PG8_SB(b, h) + boff + n * 2048 + k * 1024); } while (0)
; #define PG8_MMA(ai, bj, At, Bt) do { __builtin_amdgcn_s_setprio(1); _Pragma("unroll") for (int m = 0; m < 4; ++m) _Pragma("unroll") for (int n = 0; n < 2; ++n) _Pragma("unroll") for (int k = 0; k < 2; ++k) \
;         acc[ai][bj][m][n] = __builtin_amdgcn_mfma_f32_16x16x32_bf16(Bt[n][k], At[m][k], acc[ai][bj][m][n], 0, 0, 0); __builtin_amdgcn_s_setprio(0); } while (0)
; #define PG8_BAR __builtin_amdgcn_s_barrier()
;     ...
;         for (int t = 0; t < nt; t += 2) {
;             const bool last = (t == nt - 2);
;             const char* a1 = AS.tile(cur, t + 1);
;             const char* a2 = last ? AS.tile(nu, 0) : AS.tile(cur, t + 2); const char* b2 = last ? nB : cB + (size_t)(t + 2) * kstep;
;             const char* a3 = last ? AS.tile(nu, 1) : AS.tile(cur, t + 3); const char* b3 = b2 + kstep;
;             PG8_LDB(B0, 0, 0); PG8_LDB(B1, 0, 1); PG8_SCHED; PG8_LDA(At, 0, 0); PG8_STAGE(PG8_SA(1, 1), a1 + hstepA, voffA);
;             PG8_WAIT_V(8); PG8_WAIT_L(0); PG8_BAR; PG8_MMA(0, 0, At, B0); PG8_MMA(0, 1, At, B1); PG8_BAR; PG8_SCHED;
;             PG8_LDA(At, 0, 1); PG8_STAGE(PG8_SB(0, 0), b2, voffB); PG8_STAGE(PG8_SB(0, 1), b2 + hstepB, voffB); PG8_STAGE(PG8_SA(0, 0), a2, voffA);
;             PG8_WAIT_V(8); PG8_WAIT_L(0); PG8_BAR; PG8_MMA(1, 0, At, B0); PG8_MMA(1, 1, At, B1); PG8_BAR; PG8_SCHED;
.Lpeel_534:
	s_add_i32 s68, s2, 2
	s_add_u32 s3, s82, s64
	s_addc_u32 s20, s83, s65
	s_add_u32 s69, s3, 0x100
	s_addc_u32 s21, s20, 0
	s_add_u32 s70, s82, s66
	s_addc_u32 s71, s83, s67
	s_add_u32 s72, s3, 0x180
	s_addc_u32 s3, s20, 0
	s_add_i32 s73, 0, 0x10000
	s_add_i32 s74, 0, 0x14000
	v_add_u32_e32 v108, s73, v212
	v_add_u32_e32 v152, s74, v212
	ds_read_b128 v[76:79], v108
	ds_read_b128 v[88:91], v108 offset:1024
	ds_read_b128 v[100:103], v108 offset:2048
	ds_read_b128 v[108:111], v108 offset:3072
	ds_read_b128 v[124:127], v152
	ds_read_b128 v[128:131], v152 offset:1024
	ds_read_b128 v[144:147], v152 offset:2048
	ds_read_b128 v[152:155], v152 offset:3072
	s_cmp_eq_u32 s51, s2
	s_cselect_b32 s2, s60, s72
	s_cselect_b32 s3, s61, s3
	s_cselect_b32 s71, s41, s71
	s_cselect_b32 s70, s40, s70
	s_cselect_b32 s21, s59, s21
	s_cselect_b32 s20, s1, s69
	v_lshl_add_u64 v[222:223], s[82:83], 0, v[64:65]
	s_add_i32 m0, s35, 0xc000
	ds_read_b128 v[156:159], v241
	ds_read_b128 v[168:171], v241 offset:1024
	ds_read_b128 v[172:175], v241 offset:2048
	ds_read_b128 v[176:179], v241 offset:3072
	ds_read_b128 v[180:183], v241 offset:4096
	ds_read_b128 v[184:187], v241 offset:5120
	ds_read_b128 v[188:191], v241 offset:6144
	ds_read_b128 v[218:221], v241 offset:7168
	global_load_lds_dwordx4 v[222:223], off
	v_lshl_add_u64 v[222:223], s[82:83], 0, v[66:67]
	s_add_i32 m0, s35, 0xe000
	s_nop 0
	global_load_lds_dwordx4 v[222:223], off
	s_waitcnt vmcnt(8)
	s_waitcnt lgkmcnt(0)
	s_barrier
	s_setprio 1
	s_waitcnt lgkmcnt(0)
	v_mfma_f32_16x16x32_bf16 v[164:167], v[76:79], v[156:159], 0
	v_mfma_f32_16x16x32_bf16 v[160:163], v[100:103], v[156:159], 0
	v_mfma_f32_16x16x32_bf16 v[136:139], v[76:79], v[172:175], 0
	v_mfma_f32_16x16x32_bf16 v[132:135], v[100:103], v[172:175], 0
	v_mfma_f32_16x16x32_bf16 v[112:115], v[76:79], v[180:183], 0
	v_mfma_f32_16x16x32_bf16 v[104:107], v[100:103], v[180:183], 0
	v_mfma_f32_16x16x32_bf16 v[84:87], v[76:79], v[188:191], 0
	v_mfma_f32_16x16x32_bf16 v[80:83], v[100:103], v[188:191], 0
	v_mfma_f32_16x16x32_bf16 v[164:167], v[88:91], v[168:171], v[164:167]
	v_mfma_f32_16x16x32_bf16 v[160:163], v[108:111], v[168:171], v[160:163]
	v_mfma_f32_16x16x32_bf16 v[136:139], v[88:91], v[176:179], v[136:139]
	v_mfma_f32_16x16x32_bf16 v[132:135], v[108:111], v[176:179], v[132:135]
	v_mfma_f32_16x16x32_bf16 v[112:115], v[88:91], v[184:187], v[112:115]
	v_mfma_f32_16x16x32_bf16 v[104:107], v[108:111], v[184:187], v[104:107]
	v_mfma_f32_16x16x32_bf16 v[84:87], v[88:91], v[218:221], v[84:87]
	v_mfma_f32_16x16x32_bf16 v[80:83], v[108:111], v[218:221], v[80:83]
	s_setprio 0
	s_setprio 1
	v_mfma_f32_16x16x32_bf16 v[148:151], v[124:127], v[156:159], 0
	v_mfma_f32_16x16x32_bf16 v[140:143], v[144:147], v[156:159], 0
	v_mfma_f32_16x16x32_bf16 v[120:123], v[124:127], v[172:175], 0
	v_mfma_f32_16x16x32_bf16 v[116:119], v[144:147], v[172:175], 0
	v_mfma_f32_16x16x32_bf16 v[96:99], v[124:127], v[180:183], 0
	v_mfma_f32_16x16x32_bf16 v[92:95], v[144:147], v[180:183], 0
	v_mfma_f32_16x16x32_bf16 v[72:75], v[124:127], v[188:191], 0
	v_mfma_f32_16x16x32_bf16 v[68:71], v[144:147], v[188:191], 0
	v_mfma_f32_16x16x32_bf16 v[148:151], v[128:131], v[168:171], v[148:151]
	v_mfma_f32_16x16x32_bf16 v[140:143], v[152:155], v[168:171], v[140:143]
	v_mfma_f32_16x16x32_bf16 v[120:123], v[128:131], v[176:179], v[120:123]
	v_mfma_f32_16x16x32_bf16 v[116:119], v[152:155], v[176:179], v[116:119]
	v_mfma_f32_16x16x32_bf16 v[96:99], v[128:131], v[184:187], v[96:99]
	v_mfma_f32_16x16x32_bf16 v[92:95], v[152:155], v[184:187], v[92:95]
	v_mfma_f32_16x16x32_bf16 v[72:75], v[128:131], v[218:221], v[72:75]
	v_mfma_f32_16x16x32_bf16 v[68:71], v[152:155], v[218:221], v[68:71]
	s_setprio 0
	s_barrier
	s_add_i32 s69, s73, s25
	v_lshl_add_u64 v[222:223], s[70:71], 0, v[196:197]
	s_mov_b32 m0, s69
	ds_read_b128 v[156:159], v241 offset:16384
	ds_read_b128 v[168:171], v241 offset:17408
	ds_read_b128 v[172:175], v241 offset:18432
	ds_read_b128 v[176:179], v241 offset:19456
	ds_read_b128 v[180:183], v241 offset:20480
	ds_read_b128 v[184:187], v241 offset:21504
	ds_read_b128 v[188:191], v241 offset:22528
	ds_read_b128 v[218:221], v241 offset:23552
	global_load_lds_dwordx4 v[222:223], off
	s_add_i32 m0, s69, 0x2000
	v_lshl_add_u64 v[224:225], s[70:71], 0, v[192:193]
	s_add_u32 s70, s70, s24
	s_addc_u32 s71, s71, 0
	s_add_i32 s69, s74, s25
	global_load_lds_dwordx4 v[224:225], off
	v_lshl_add_u64 v[244:245], s[70:71], 0, v[196:197]
	s_mov_b32 m0, s69
	v_lshl_add_u64 v[246:247], s[70:71], 0, v[192:193]
	global_load_lds_dwordx4 v[244:245], off
	s_add_i32 m0, s69, 0x2000
	v_lshl_add_u64 v[248:249], s[20:21], 0, v[198:199]
	global_load_lds_dwordx4 v[246:247], off
	s_mov_b32 m0, s35
	s_nop 0
	global_load_lds_dwordx4 v[248:249], off
	v_lshl_add_u64 v[248:249], s[20:21], 0, v[194:195]
	s_mov_b32 m0, s44
	s_nop 0
	global_load_lds_dwordx4 v[248:249], off
	s_waitcnt vmcnt(8)
	s_waitcnt lgkmcnt(0)
	s_barrier
; #define PG8_STAGE(bufoff, gbase, voff) do { _Pragma("unroll") for (int _i = 0; _i < 2; ++_i) \
;         __builtin_amdgcn_global_load_lds((const unsigned*)((const char*)(gbase) + (voff)[_i]), (PG8_LAS unsigned*)(lds + (bufoff) + ldsw + _i * 8192), 16, 0, 0); } while (0)
; #define PG8_LDA(dst, b, h) do { _Pragma("unroll") for (int m = 0; m < 4; ++m) _Pragma("unroll") for (int k = 0; k < 2; ++k) dst[m][k] = *(const PG8_LAS bf16x8*)(lds + PG8_SA(b, h) + aoff + m * 2048 + k * 1024); } while (0)
; #define PG8_LDB(dst, b, h) do { _Pragma("unroll") for (int n = 0; n < 2; ++n) _Pragma("unroll") for (int k = 0; k < 2; ++k) dst[n][k] = *(const PG8_LAS bf16x8*)(lds + PG8_SB(b, h) + boff + n * 2048 + k * 1024); } while (0)
; #define PG8_MMA(ai, bj, At, Bt) do { __builtin_amdgcn_s_setprio(1); _Pragma("unroll") for (int m = 0; m < 4; ++m) _Pragma("unroll") for (int n = 0; n < 2; ++n) _Pragma("unroll") for (int k = 0; k < 2; ++k) \
;         acc[ai][bj][m][n] = __builtin_amdgcn_mfma_f32_16x16x32_bf16(Bt[n][k], At[m][k], acc[ai][bj][m][n], 0, 0, 0); __builtin_amdgcn_s_setprio(0); } while (0)
; #define PG8_WAIT_V(n) asm volatile("s_waitcnt vmcnt(" #n ")" ::: "memory")
; #define PG8_WAIT_L(n) asm volatile("s_waitcnt lgkmcnt(" #n ")" ::: "memory")
; #define PG8_BAR __builtin_amdgcn_s_barrier()
; #define PG8_SCHED __builtin_amdgcn_sched_barrier(0)
;     ...
;             PG8_WAIT_V(8); PG8_WAIT_L(0); PG8_BAR; PG8_MMA(1, 0, At, B0); PG8_MMA(1, 1, At, B1); PG8_BAR; PG8_SCHED;
;             PG8_LDB(B0, 1, 0); PG8_LDB(B1, 1, 1); PG8_SCHED; PG8_LDA(At, 1, 0); PG8_STAGE(PG8_SA(0, 1), a2 + hstepA, voffA);
;             PG8_WAIT_V(8); PG8_WAIT_L(0); PG8_BAR; PG8_MMA(0, 0, At, B0); PG8_MMA(0, 1, At, B1); PG8_BAR; PG8_SCHED;
	s_setprio 1
	s_waitcnt lgkmcnt(0)
	v_mfma_f32_16x16x32_bf16 v[60:63], v[76:79], v[156:159], 0
	v_mfma_f32_16x16x32_bf16 v[56:59], v[100:103], v[156:159], 0
	v_mfma_f32_16x16x32_bf16 v[44:47], v[76:79], v[172:175], 0
	v_mfma_f32_16x16x32_bf16 v[40:43], v[100:103], v[172:175], 0
	v_mfma_f32_16x16x32_bf16 v[28:31], v[76:79], v[180:183], 0
	v_mfma_f32_16x16x32_bf16 v[24:27], v[100:103], v[180:183], 0
	v_mfma_f32_16x16x32_bf16 v[12:15], v[76:79], v[188:191], 0
	v_mfma_f32_16x16x32_bf16 v[8:11], v[100:103], v[188:191], 0
	v_mfma_f32_16x16x32_bf16 v[60:63], v[88:91], v[168:171], v[60:63]
	v_mfma_f32_16x16x32_bf16 v[56:59], v[108:111], v[168:171], v[56:59]
	v_mfma_f32_16x16x32_bf16 v[44:47], v[88:91], v[176:179], v[44:47]
	v_mfma_f32_16x16x32_bf16 v[40:43], v[108:111], v[176:179], v[40:43]
	v_mfma_f32_16x16x32_bf16 v[28:31], v[88:91], v[184:187], v[28:31]
	v_mfma_f32_16x16x32_bf16 v[24:27], v[108:111], v[184:187], v[24:27]
	v_mfma_f32_16x16x32_bf16 v[12:15], v[88:91], v[218:221], v[12:15]
	v_mfma_f32_16x16x32_bf16 v[8:11], v[108:111], v[218:221], v[8:11]
	s_setprio 0
	s_setprio 1
	v_mfma_f32_16x16x32_bf16 v[52:55], v[124:127], v[156:159], 0
	v_mfma_f32_16x16x32_bf16 v[48:51], v[144:147], v[156:159], 0
	v_mfma_f32_16x16x32_bf16 v[36:39], v[124:127], v[172:175], 0
	v_mfma_f32_16x16x32_bf16 v[32:35], v[144:147], v[172:175], 0
	v_mfma_f32_16x16x32_bf16 v[20:23], v[124:127], v[180:183], 0
	v_mfma_f32_16x16x32_bf16 v[16:19], v[144:147], v[180:183], 0
	v_mfma_f32_16x16x32_bf16 v[4:7], v[124:127], v[188:191], 0
	v_mfma_f32_16x16x32_bf16 v[0:3], v[144:147], v[188:191], 0
	v_mfma_f32_16x16x32_bf16 v[52:55], v[128:131], v[168:171], v[52:55]
	v_mfma_f32_16x16x32_bf16 v[48:51], v[152:155], v[168:171], v[48:51]
	v_mfma_f32_16x16x32_bf16 v[36:39], v[128:131], v[176:179], v[36:39]
	v_mfma_f32_16x16x32_bf16 v[32:35], v[152:155], v[176:179], v[32:35]
	v_mfma_f32_16x16x32_bf16 v[20:23], v[128:131], v[184:187], v[20:23]
	v_mfma_f32_16x16x32_bf16 v[16:19], v[152:155], v[184:187], v[16:19]
	v_mfma_f32_16x16x32_bf16 v[4:7], v[128:131], v[218:221], v[4:7]
	v_mfma_f32_16x16x32_bf16 v[0:3], v[152:155], v[218:221], v[0:3]
	s_setprio 0
	s_barrier
	s_add_i32 s69, 0, 0x18000
	s_add_i32 s70, 0, 0x1c000
	v_add_u32_e32 v108, s69, v212
	v_add_u32_e32 v152, s70, v212
	ds_read_b128 v[76:79], v108
	ds_read_b128 v[88:91], v108 offset:1024
	ds_read_b128 v[100:103], v108 offset:2048
	ds_read_b128 v[108:111], v108 offset:3072
	ds_read_b128 v[124:127], v152
	ds_read_b128 v[128:131], v152 offset:1024
	ds_read_b128 v[144:147], v152 offset:2048
	ds_read_b128 v[152:155], v152 offset:3072
	s_add_u32 s20, s20, s24
	s_addc_u32 s21, s21, 0
	s_mov_b32 m0, s45
	v_lshl_add_u64 v[248:249], s[20:21], 0, v[198:199]
	ds_read_b128 v[156:159], v241 offset:32768
	ds_read_b128 v[168:171], v241 offset:33792
	ds_read_b128 v[172:175], v241 offset:34816
	ds_read_b128 v[176:179], v241 offset:35840
	ds_read_b128 v[180:183], v241 offset:36864
	ds_read_b128 v[184:187], v241 offset:37888
	ds_read_b128 v[188:191], v241 offset:38912
	ds_read_b128 v[218:221], v241 offset:39936
	global_load_lds_dwordx4 v[248:249], off
	v_lshl_add_u64 v[248:249], s[20:21], 0, v[194:195]
	s_mov_b32 m0, s46
	s_nop 0
	global_load_lds_dwordx4 v[248:249], off
	s_waitcnt vmcnt(8)
	s_waitcnt lgkmcnt(0)
	s_barrier
	s_setprio 1
	s_waitcnt lgkmcnt(0)
	v_mfma_f32_16x16x32_bf16 v[164:167], v[76:79], v[156:159], v[164:167]
	v_mfma_f32_16x16x32_bf16 v[160:163], v[100:103], v[156:159], v[160:163]
	v_mfma_f32_16x16x32_bf16 v[136:139], v[76:79], v[172:175], v[136:139]
	v_mfma_f32_16x16x32_bf16 v[132:135], v[100:103], v[172:175], v[132:135]
	v_mfma_f32_16x16x32_bf16 v[112:115], v[76:79], v[180:183], v[112:115]
	v_mfma_f32_16x16x32_bf16 v[104:107], v[100:103], v[180:183], v[104:107]
	v_mfma_f32_16x16x32_bf16 v[84:87], v[76:79], v[188:191], v[84:87]
	v_mfma_f32_16x16x32_bf16 v[80:83], v[100:103], v[188:191], v[80:83]
	v_mfma_f32_16x16x32_bf16 v[164:167], v[88:91], v[168:171], v[164:167]
	v_mfma_f32_16x16x32_bf16 v[160:163], v[108:111], v[168:171], v[160:163]
	v_mfma_f32_16x16x32_bf16 v[136:139], v[88:91], v[176:179], v[136:139]
	v_mfma_f32_16x16x32_bf16 v[132:135], v[108:111], v[176:179], v[132:135]
	v_mfma_f32_16x16x32_bf16 v[112:115], v[88:91], v[184:187], v[112:115]
	v_mfma_f32_16x16x32_bf16 v[104:107], v[108:111], v[184:187], v[104:107]
	v_mfma_f32_16x16x32_bf16 v[84:87], v[88:91], v[218:221], v[84:87]
	v_mfma_f32_16x16x32_bf16 v[80:83], v[108:111], v[218:221], v[80:83]
	s_setprio 0
	s_setprio 1
	v_mfma_f32_16x16x32_bf16 v[148:151], v[124:127], v[156:159], v[148:151]
	v_mfma_f32_16x16x32_bf16 v[140:143], v[144:147], v[156:159], v[140:143]
	v_mfma_f32_16x16x32_bf16 v[120:123], v[124:127], v[172:175], v[120:123]
	v_mfma_f32_16x16x32_bf16 v[116:119], v[144:147], v[172:175], v[116:119]
	v_mfma_f32_16x16x32_bf16 v[96:99], v[124:127], v[180:183], v[96:99]
	v_mfma_f32_16x16x32_bf16 v[92:95], v[144:147], v[180:183], v[92:95]
	v_mfma_f32_16x16x32_bf16 v[72:75], v[124:127], v[188:191], v[72:75]
	v_mfma_f32_16x16x32_bf16 v[68:71], v[144:147], v[188:191], v[68:71]
	v_mfma_f32_16x16x32_bf16 v[148:151], v[128:131], v[168:171], v[148:151]
	v_mfma_f32_16x16x32_bf16 v[140:143], v[152:155], v[168:171], v[140:143]
	v_mfma_f32_16x16x32_bf16 v[120:123], v[128:131], v[176:179], v[120:123]
	v_mfma_f32_16x16x32_bf16 v[116:119], v[152:155], v[176:179], v[116:119]
	v_mfma_f32_16x16x32_bf16 v[96:99], v[128:131], v[184:187], v[96:99]
	v_mfma_f32_16x16x32_bf16 v[92:95], v[152:155], v[184:187], v[92:95]
	v_mfma_f32_16x16x32_bf16 v[72:75], v[128:131], v[218:221], v[72:75]
	v_mfma_f32_16x16x32_bf16 v[68:71], v[152:155], v[218:221], v[68:71]
	s_setprio 0
	s_barrier
; #define PG8_STAGE(bufoff, gbase, voff) do { _Pragma("unroll") for (int _i = 0; _i < 2; ++_i) \
;         __builtin_amdgcn_global_load_lds((const unsigned*)((const char*)(gbase) + (voff)[_i]), (PG8_LAS unsigned*)(lds + (bufoff) + ldsw + _i * 8192), 16, 0, 0); } while (0)
; #define PG8_LDA(dst, b, h) do { _Pragma("unroll") for (int m = 0; m < 4; ++m) _Pragma("unroll") for (int k = 0; k < 2; ++k) dst[m][k] = *(const PG8_LAS bf16x8*)(lds + PG8_SA(b, h) + aoff + m * 2048 + k * 1024); } while (0)
; #define PG8_MMA(ai, bj, At, Bt) do { __builtin_amdgcn_s_setprio(1); _Pragma("unroll") for (int m = 0; m < 4; ++m) _Pragma("unroll") for (int n = 0; n < 2; ++n) _Pragma("unroll") for (int k = 0; k < 2; ++k) \
;         acc[ai][bj][m][n] = __builtin_amdgcn_mfma_f32_16x16x32_bf16(Bt[n][k], At[m][k], acc[ai][bj][m][n], 0, 0, 0); __builtin_amdgcn_s_setprio(0); } while (0)
; #define PG8_WAIT_V(n) asm volatile("s_waitcnt vmcnt(" #n ")" ::: "memory")
; #define PG8_WAIT_L(n) asm volatile("s_waitcnt lgkmcnt(" #n ")" ::: "memory")
; #define PG8_BAR __builtin_amdgcn_s_barrier()
; #define PG8_SCHED __builtin_amdgcn_sched_barrier(0)
;     ...
;         for (int t = 0; t < nt; t += 2) {
;     ...
;             PG8_LDA(At, 1, 1); PG8_STAGE(PG8_SB(1, 0), b3, voffB); PG8_STAGE(PG8_SB(1, 1), b3 + hstepB, voffB); PG8_STAGE(PG8_SA(1, 0), a3, voffA);
;             PG8_WAIT_V(8); PG8_WAIT_L(0); PG8_BAR; PG8_MMA(1, 0, At, B0); PG8_MMA(1, 1, At, B1); PG8_BAR; PG8_SCHED;
	s_add_i32 s20, s69, s25
	v_lshl_add_u64 v[222:223], v[222:223], 0, s[76:77]
	s_mov_b32 m0, s20
	ds_read_b128 v[156:159], v241 offset:49152
	ds_read_b128 v[168:171], v241 offset:50176
	ds_read_b128 v[172:175], v241 offset:51200
	ds_read_b128 v[176:179], v241 offset:52224
	ds_read_b128 v[180:183], v241 offset:53248
	ds_read_b128 v[184:187], v241 offset:54272
	ds_read_b128 v[188:191], v241 offset:55296
	ds_read_b128 v[218:221], v241 offset:56320
	global_load_lds_dwordx4 v[222:223], off
	v_lshl_add_u64 v[222:223], v[224:225], 0, s[76:77]
	s_add_i32 m0, s20, 0x2000
	s_add_i32 s20, s70, s25
	global_load_lds_dwordx4 v[222:223], off
	v_lshl_add_u64 v[222:223], v[244:245], 0, s[76:77]
	s_mov_b32 m0, s20
	s_nop 0
	global_load_lds_dwordx4 v[222:223], off
	v_lshl_add_u64 v[222:223], v[246:247], 0, s[76:77]
	s_add_i32 m0, s20, 0x2000
	s_nop 0
	global_load_lds_dwordx4 v[222:223], off
	v_lshl_add_u64 v[222:223], s[2:3], 0, v[198:199]
	s_mov_b32 m0, s47
	s_nop 0
	global_load_lds_dwordx4 v[222:223], off
	v_lshl_add_u64 v[222:223], s[2:3], 0, v[194:195]
	s_mov_b32 m0, s48
	s_nop 0
	global_load_lds_dwordx4 v[222:223], off
	s_waitcnt vmcnt(8)
	s_waitcnt lgkmcnt(0)
	s_barrier
	s_setprio 1
	s_waitcnt lgkmcnt(0)
	v_mfma_f32_16x16x32_bf16 v[60:63], v[76:79], v[156:159], v[60:63]
	v_mfma_f32_16x16x32_bf16 v[56:59], v[100:103], v[156:159], v[56:59]
	v_mfma_f32_16x16x32_bf16 v[44:47], v[76:79], v[172:175], v[44:47]
	v_mfma_f32_16x16x32_bf16 v[40:43], v[100:103], v[172:175], v[40:43]
	v_mfma_f32_16x16x32_bf16 v[28:31], v[76:79], v[180:183], v[28:31]
	v_mfma_f32_16x16x32_bf16 v[24:27], v[100:103], v[180:183], v[24:27]
	v_mfma_f32_16x16x32_bf16 v[12:15], v[76:79], v[188:191], v[12:15]
	v_mfma_f32_16x16x32_bf16 v[8:11], v[100:103], v[188:191], v[8:11]
	v_mfma_f32_16x16x32_bf16 v[60:63], v[88:91], v[168:171], v[60:63]
	v_mfma_f32_16x16x32_bf16 v[56:59], v[108:111], v[168:171], v[56:59]
	v_mfma_f32_16x16x32_bf16 v[44:47], v[88:91], v[176:179], v[44:47]
	v_mfma_f32_16x16x32_bf16 v[40:43], v[108:111], v[176:179], v[40:43]
	v_mfma_f32_16x16x32_bf16 v[28:31], v[88:91], v[184:187], v[28:31]
	v_mfma_f32_16x16x32_bf16 v[24:27], v[108:111], v[184:187], v[24:27]
	v_mfma_f32_16x16x32_bf16 v[12:15], v[88:91], v[218:221], v[12:15]
	v_mfma_f32_16x16x32_bf16 v[8:11], v[108:111], v[218:221], v[8:11]
	s_setprio 0
	s_setprio 1
	v_mfma_f32_16x16x32_bf16 v[52:55], v[124:127], v[156:159], v[52:55]
	v_mfma_f32_16x16x32_bf16 v[48:51], v[144:147], v[156:159], v[48:51]
	v_mfma_f32_16x16x32_bf16 v[36:39], v[124:127], v[172:175], v[36:39]
	v_mfma_f32_16x16x32_bf16 v[32:35], v[144:147], v[172:175], v[32:35]
	v_mfma_f32_16x16x32_bf16 v[20:23], v[124:127], v[180:183], v[20:23]
	v_mfma_f32_16x16x32_bf16 v[16:19], v[144:147], v[180:183], v[16:19]
	v_mfma_f32_16x16x32_bf16 v[4:7], v[124:127], v[188:191], v[4:7]
	v_mfma_f32_16x16x32_bf16 v[0:3], v[144:147], v[188:191], v[0:3]
	v_mfma_f32_16x16x32_bf16 v[52:55], v[128:131], v[168:171], v[52:55]
	v_mfma_f32_16x16x32_bf16 v[48:51], v[152:155], v[168:171], v[48:51]
	v_mfma_f32_16x16x32_bf16 v[36:39], v[128:131], v[176:179], v[36:39]
	v_mfma_f32_16x16x32_bf16 v[32:35], v[152:155], v[176:179], v[32:35]
	v_mfma_f32_16x16x32_bf16 v[20:23], v[128:131], v[184:187], v[20:23]
	v_mfma_f32_16x16x32_bf16 v[16:19], v[152:155], v[184:187], v[16:19]
	v_mfma_f32_16x16x32_bf16 v[4:7], v[128:131], v[218:221], v[4:7]
	v_mfma_f32_16x16x32_bf16 v[0:3], v[152:155], v[218:221], v[0:3]
	s_setprio 0
	s_barrier
	s_add_u32 s64, s64, 0x100
	s_addc_u32 s65, s65, 0
	s_add_u32 s66, s66, 0x100
	s_addc_u32 s67, s67, 0
	v_lshl_add_u64 v[64:65], v[64:65], 0, s[78:79]
	v_lshl_add_u64 v[66:67], v[66:67], 0, s[78:79]
	s_cmp_ge_u32 s68, s50
	s_mov_b32 s2, s68
	s_cbranch_scc0 .LBB0_534
	s_branch .Lpeel_exit_534
	.p2alignl 6, 3212836864

;     __device__ __forceinline__ const char* tile(const Unit& u, int t) const { return A + (size_t)u.pm * 2 * hstep() + (size_t)t * (BK * 2); }
;     __device__ __forceinline__ const char* tile(const Unit& u, int t) const { return U + (long)(t >> 2) * xoff + (size_t)u.pn * (1024 * 512) + (size_t)u.pm * 2 * hstep() + (size_t)(t & 3) * (BK * 2); }
; #define PG8_STAGE(bufoff, gbase, voff) do { _Pragma("unroll") for (int _i = 0; _i < 2; ++_i) \
;         __builtin_amdgcn_global_load_lds((const unsigned*)((const char*)(gbase) + (voff)[_i]), (PG8_LAS unsigned*)(lds + (bufoff) + ldsw + _i * 8192), 16, 0, 0); } while (0)
; #define PG8_LDA(dst, b, h) do { _Pragma("unroll") for (int m = 0; m < 4; ++m) _Pragma("unroll") for (int k = 0; k < 2; ++k) dst[m][k] = *(const PG8_LAS bf16x8*)(lds + PG8_SA(b, h) + aoff + m * 2048 + k * 1024); } while (0)
; #define PG8_LDB(dst, b, h) do { _Pragma("unroll") for (int n = 0; n < 2; ++n) _Pragma("unroll") for (int k = 0; k < 2; ++k) dst[n][k] = *(const PG8_LAS bf16x8*)(lds + PG8_SB(b, h) + boff + n * 2048 + k * 1024); } while (0)
; #define PG8_MMA(ai, bj, At, Bt) do { __builtin_amdgcn_s_setprio(1); _Pragma("unroll") for (int m = 0; m < 4; ++m) _Pragma("unroll") for (int n = 0; n < 2; ++n) _Pragma("unroll") for (int k = 0; k < 2; ++k) \
;         acc[ai][bj][m][n] = __builtin_amdgcn_mfma_f32_16x16x32_bf16(Bt[n][k], At[m][k], acc[ai][bj][m][n], 0, 0, 0); __builtin_amdgcn_s_setprio(0); } while (0)
; #define PG8_BAR __builtin_amdgcn_s_barrier()
;     ...
;         for (int t = 0; t < nt; t += 2) {
;             const bool last = (t == nt - 2);
;             const char* a1 = AS.tile(cur, t + 1);
;             const char* a2 = last ? AS.tile(nu, 0) : AS.tile(cur, t + 2); const char* b2 = last ? nB : cB + (size_t)(t + 2) * kstep;
;             const char* a3 = last ? AS.tile(nu, 1) : AS.tile(cur, t + 3); const char* b3 = b2 + kstep;
;             PG8_LDB(B0, 0, 0); PG8_LDB(B1, 0, 1); PG8_SCHED; PG8_LDA(At, 0, 0); PG8_STAGE(PG8_SA(1, 1), a1 + hstepA, voffA);
;             PG8_WAIT_V(8); PG8_WAIT_L(0); PG8_BAR; PG8_MMA(0, 0, At, B0); PG8_MMA(0, 1, At, B1); PG8_BAR; PG8_SCHED;
;             PG8_LDA(At, 0, 1); PG8_STAGE(PG8_SB(0, 0), b2, voffB); PG8_STAGE(PG8_SB(0, 1), b2 + hstepB, voffB); PG8_STAGE(PG8_SA(0, 0), a2, voffA);
;             PG8_WAIT_V(8); PG8_WAIT_L(0); PG8_BAR; PG8_MMA(1, 0, At, B0); PG8_MMA(1, 1, At, B1); PG8_BAR; PG8_SCHED;
.Lpeel_702:
	s_add_u32 s20, s40, s2
	s_addc_u32 s21, s41, s3
	s_add_u32 s26, s20, 0x400100
	s_addc_u32 s27, s21, 0
	s_add_u32 s24, s42, s2
	s_addc_u32 s25, s43, s3
	s_add_u32 s20, s20, 0x400180
	s_addc_u32 s21, s21, 0
	s_add_i32 s63, 0, 0x10000
	s_add_i32 s66, 0, 0x14000
	v_add_u32_e32 v156, s63, v185
	v_add_u32_e32 v172, s66, v185
	ds_read_b128 v[132:135], v156
	ds_read_b128 v[136:139], v156 offset:1024
	ds_read_b128 v[140:143], v156 offset:2048
	ds_read_b128 v[156:159], v156 offset:3072
	ds_read_b128 v[160:163], v172
	ds_read_b128 v[164:167], v172 offset:1024
	ds_read_b128 v[168:171], v172 offset:2048
	ds_read_b128 v[172:175], v172 offset:3072
	s_cmpk_eq_i32 s2, 0x700
	s_cselect_b32 s21, s31, s21
	s_cselect_b32 s20, s30, s20
	s_cselect_b32 s25, s28, s25
	s_cselect_b32 s24, s1, s24
	s_cselect_b32 s27, s29, s27
	s_cselect_b32 s26, s19, s26
	v_lshl_add_u64 v[238:239], v[128:129], 0, s[2:3]
	s_add_i32 m0, s49, 0xc000
	ds_read_b128 v[176:179], v190
	ds_read_b128 v[180:183], v190 offset:1024
	ds_read_b128 v[192:195], v190 offset:2048
	ds_read_b128 v[196:199], v190 offset:3072
	ds_read_b128 v[200:203], v190 offset:4096
	ds_read_b128 v[204:207], v190 offset:5120
	ds_read_b128 v[218:221], v190 offset:6144
	ds_read_b128 v[222:225], v190 offset:7168
	global_load_lds_dwordx4 v[238:239], off
	v_lshl_add_u64 v[238:239], v[130:131], 0, s[2:3]
	s_add_i32 m0, s49, 0xe000
	s_nop 0
	global_load_lds_dwordx4 v[238:239], off
	s_waitcnt vmcnt(24)
	s_waitcnt lgkmcnt(0)
	s_barrier
	s_setprio 1
	s_waitcnt lgkmcnt(0)
	v_mfma_f32_16x16x32_bf16 v[124:127], v[132:135], v[176:179], 0
	v_mfma_f32_16x16x32_bf16 v[120:123], v[140:143], v[176:179], 0
	v_mfma_f32_16x16x32_bf16 v[112:115], v[132:135], v[192:195], 0
	v_mfma_f32_16x16x32_bf16 v[104:107], v[140:143], v[192:195], 0
	v_mfma_f32_16x16x32_bf16 v[96:99], v[132:135], v[200:203], 0
	v_mfma_f32_16x16x32_bf16 v[88:91], v[140:143], v[200:203], 0
	v_mfma_f32_16x16x32_bf16 v[80:83], v[132:135], v[218:221], 0
	v_mfma_f32_16x16x32_bf16 v[72:75], v[140:143], v[218:221], 0
	v_mfma_f32_16x16x32_bf16 v[124:127], v[136:139], v[180:183], v[124:127]
	v_mfma_f32_16x16x32_bf16 v[120:123], v[156:159], v[180:183], v[120:123]
	v_mfma_f32_16x16x32_bf16 v[112:115], v[136:139], v[196:199], v[112:115]
	v_mfma_f32_16x16x32_bf16 v[104:107], v[156:159], v[196:199], v[104:107]
	v_mfma_f32_16x16x32_bf16 v[96:99], v[136:139], v[204:207], v[96:99]
	v_mfma_f32_16x16x32_bf16 v[88:91], v[156:159], v[204:207], v[88:91]
	v_mfma_f32_16x16x32_bf16 v[80:83], v[136:139], v[222:225], v[80:83]
	v_mfma_f32_16x16x32_bf16 v[72:75], v[156:159], v[222:225], v[72:75]
	s_setprio 0
	s_setprio 1
	v_mfma_f32_16x16x32_bf16 v[116:119], v[160:163], v[176:179], 0
	v_mfma_f32_16x16x32_bf16 v[108:111], v[168:171], v[176:179], 0
	v_mfma_f32_16x16x32_bf16 v[100:103], v[160:163], v[192:195], 0
	v_mfma_f32_16x16x32_bf16 v[92:95], v[168:171], v[192:195], 0
	v_mfma_f32_16x16x32_bf16 v[84:87], v[160:163], v[200:203], 0
	v_mfma_f32_16x16x32_bf16 v[76:79], v[168:171], v[200:203], 0
	v_mfma_f32_16x16x32_bf16 v[68:71], v[160:163], v[218:221], 0
	v_mfma_f32_16x16x32_bf16 v[64:67], v[168:171], v[218:221], 0
	v_mfma_f32_16x16x32_bf16 v[116:119], v[164:167], v[180:183], v[116:119]
	v_mfma_f32_16x16x32_bf16 v[108:111], v[172:175], v[180:183], v[108:111]
	v_mfma_f32_16x16x32_bf16 v[100:103], v[164:167], v[196:199], v[100:103]
	v_mfma_f32_16x16x32_bf16 v[92:95], v[172:175], v[196:199], v[92:95]
	v_mfma_f32_16x16x32_bf16 v[84:87], v[164:167], v[204:207], v[84:87]
	v_mfma_f32_16x16x32_bf16 v[76:79], v[172:175], v[204:207], v[76:79]
	v_mfma_f32_16x16x32_bf16 v[68:71], v[164:167], v[222:225], v[68:71]
	v_mfma_f32_16x16x32_bf16 v[64:67], v[172:175], v[222:225], v[64:67]
	s_setprio 0
	s_barrier
	s_add_i32 s63, s63, s48
	v_lshl_add_u64 v[238:239], s[24:25], 0, v[148:149]
	s_mov_b32 m0, s63
	ds_read_b128 v[176:179], v190 offset:16384
	ds_read_b128 v[180:183], v190 offset:17408
	ds_read_b128 v[192:195], v190 offset:18432
	ds_read_b128 v[196:199], v190 offset:19456
	ds_read_b128 v[200:203], v190 offset:20480
	ds_read_b128 v[204:207], v190 offset:21504
	ds_read_b128 v[218:221], v190 offset:22528
	ds_read_b128 v[222:225], v190 offset:23552
	global_load_lds_dwordx4 v[238:239], off
	s_add_i32 m0, s63, 0x2000
	s_add_u32 s64, s24, 0x40000
	v_lshl_add_u64 v[240:241], s[24:25], 0, v[144:145]
	s_addc_u32 s65, s25, 0
	s_add_i32 s63, s66, s48
	global_load_lds_dwordx4 v[240:241], off
	v_lshl_add_u64 v[242:243], s[64:65], 0, v[148:149]
	s_mov_b32 m0, s63
	s_nop 0
	global_load_lds_dwordx4 v[242:243], off
	v_lshl_add_u64 v[242:243], s[64:65], 0, v[144:145]
	s_add_i32 m0, s63, 0x2000
	s_nop 0
	global_load_lds_dwordx4 v[242:243], off
	v_lshl_add_u64 v[242:243], s[26:27], 0, v[150:151]
	s_mov_b32 m0, s49
	s_nop 0
	global_load_lds_dwordx4 v[242:243], off
	v_lshl_add_u64 v[242:243], s[26:27], 0, v[146:147]
	s_mov_b32 m0, s50
	s_nop 0
	global_load_lds_dwordx4 v[242:243], off
	s_waitcnt vmcnt(8)
	s_waitcnt lgkmcnt(0)
	s_barrier
; #define PG8_STAGE(bufoff, gbase, voff) do { _Pragma("unroll") for (int _i = 0; _i < 2; ++_i) \
;         __builtin_amdgcn_global_load_lds((const unsigned*)((const char*)(gbase) + (voff)[_i]), (PG8_LAS unsigned*)(lds + (bufoff) + ldsw + _i * 8192), 16, 0, 0); } while (0)
; #define PG8_LDA(dst, b, h) do { _Pragma("unroll") for (int m = 0; m < 4; ++m) _Pragma("unroll") for (int k = 0; k < 2; ++k) dst[m][k] = *(const PG8_LAS bf16x8*)(lds + PG8_SA(b, h) + aoff + m * 2048 + k * 1024); } while (0)
; #define PG8_LDB(dst, b, h) do { _Pragma("unroll") for (int n = 0; n < 2; ++n) _Pragma("unroll") for (int k = 0; k < 2; ++k) dst[n][k] = *(const PG8_LAS bf16x8*)(lds + PG8_SB(b, h) + boff + n * 2048 + k * 1024); } while (0)
; #define PG8_MMA(ai, bj, At, Bt) do { __builtin_amdgcn_s_setprio(1); _Pragma("unroll") for (int m = 0; m < 4; ++m) _Pragma("unroll") for (int n = 0; n < 2; ++n) _Pragma("unroll") for (int k = 0; k < 2; ++k) \
;         acc[ai][bj][m][n] = __builtin_amdgcn_mfma_f32_16x16x32_bf16(Bt[n][k], At[m][k], acc[ai][bj][m][n], 0, 0, 0); __builtin_amdgcn_s_setprio(0); } while (0)
; #define PG8_WAIT_V(n) asm volatile("s_waitcnt vmcnt(" #n ")" ::: "memory")
; #define PG8_WAIT_L(n) asm volatile("s_waitcnt lgkmcnt(" #n ")" ::: "memory")
; #define PG8_BAR __builtin_amdgcn_s_barrier()
; #define PG8_SCHED __builtin_amdgcn_sched_barrier(0)
;     ...
;             PG8_WAIT_V(8); PG8_WAIT_L(0); PG8_BAR; PG8_MMA(1, 0, At, B0); PG8_MMA(1, 1, At, B1); PG8_BAR; PG8_SCHED;
;             PG8_LDB(B0, 1, 0); PG8_LDB(B1, 1, 1); PG8_SCHED; PG8_LDA(At, 1, 0); PG8_STAGE(PG8_SA(0, 1), a2 + hstepA, voffA);
;             PG8_WAIT_V(8); PG8_WAIT_L(0); PG8_BAR; PG8_MMA(0, 0, At, B0); PG8_MMA(0, 1, At, B1); PG8_BAR; PG8_SCHED;
	s_setprio 1
	s_waitcnt lgkmcnt(0)
	v_mfma_f32_16x16x32_bf16 v[60:63], v[132:135], v[176:179], 0
	v_mfma_f32_16x16x32_bf16 v[56:59], v[140:143], v[176:179], 0
	v_mfma_f32_16x16x32_bf16 v[48:51], v[132:135], v[192:195], 0
	v_mfma_f32_16x16x32_bf16 v[40:43], v[140:143], v[192:195], 0
	v_mfma_f32_16x16x32_bf16 v[32:35], v[132:135], v[200:203], 0
	v_mfma_f32_16x16x32_bf16 v[24:27], v[140:143], v[200:203], 0
	v_mfma_f32_16x16x32_bf16 v[16:19], v[132:135], v[218:221], 0
	v_mfma_f32_16x16x32_bf16 v[8:11], v[140:143], v[218:221], 0
	v_mfma_f32_16x16x32_bf16 v[60:63], v[136:139], v[180:183], v[60:63]
	v_mfma_f32_16x16x32_bf16 v[56:59], v[156:159], v[180:183], v[56:59]
	v_mfma_f32_16x16x32_bf16 v[48:51], v[136:139], v[196:199], v[48:51]
	v_mfma_f32_16x16x32_bf16 v[40:43], v[156:159], v[196:199], v[40:43]
	v_mfma_f32_16x16x32_bf16 v[32:35], v[136:139], v[204:207], v[32:35]
	v_mfma_f32_16x16x32_bf16 v[24:27], v[156:159], v[204:207], v[24:27]
	v_mfma_f32_16x16x32_bf16 v[16:19], v[136:139], v[222:225], v[16:19]
	v_mfma_f32_16x16x32_bf16 v[8:11], v[156:159], v[222:225], v[8:11]
	s_setprio 0
	s_setprio 1
	v_mfma_f32_16x16x32_bf16 v[52:55], v[160:163], v[176:179], 0
	v_mfma_f32_16x16x32_bf16 v[44:47], v[168:171], v[176:179], 0
	v_mfma_f32_16x16x32_bf16 v[36:39], v[160:163], v[192:195], 0
	v_mfma_f32_16x16x32_bf16 v[28:31], v[168:171], v[192:195], 0
	v_mfma_f32_16x16x32_bf16 v[20:23], v[160:163], v[200:203], 0
	v_mfma_f32_16x16x32_bf16 v[12:15], v[168:171], v[200:203], 0
	v_mfma_f32_16x16x32_bf16 v[4:7], v[160:163], v[218:221], 0
	v_mfma_f32_16x16x32_bf16 v[0:3], v[168:171], v[218:221], 0
	v_mfma_f32_16x16x32_bf16 v[52:55], v[164:167], v[180:183], v[52:55]
	v_mfma_f32_16x16x32_bf16 v[44:47], v[172:175], v[180:183], v[44:47]
	v_mfma_f32_16x16x32_bf16 v[36:39], v[164:167], v[196:199], v[36:39]
	v_mfma_f32_16x16x32_bf16 v[28:31], v[172:175], v[196:199], v[28:31]
	v_mfma_f32_16x16x32_bf16 v[20:23], v[164:167], v[204:207], v[20:23]
	v_mfma_f32_16x16x32_bf16 v[12:15], v[172:175], v[204:207], v[12:15]
	v_mfma_f32_16x16x32_bf16 v[4:7], v[164:167], v[222:225], v[4:7]
	v_mfma_f32_16x16x32_bf16 v[0:3], v[172:175], v[222:225], v[0:3]
	s_setprio 0
	s_barrier
	s_add_i32 s63, 0, 0x18000
	s_add_i32 s64, 0, 0x1c000
	v_add_u32_e32 v156, s63, v185
	v_add_u32_e32 v172, s64, v185
	ds_read_b128 v[132:135], v156
	ds_read_b128 v[136:139], v156 offset:1024
	ds_read_b128 v[140:143], v156 offset:2048
	ds_read_b128 v[156:159], v156 offset:3072
	ds_read_b128 v[160:163], v172
	ds_read_b128 v[164:167], v172 offset:1024
	ds_read_b128 v[168:171], v172 offset:2048
	ds_read_b128 v[172:175], v172 offset:3072
	s_add_u32 s26, s26, 0x40000
	s_addc_u32 s27, s27, 0
	s_mov_b32 m0, s51
	v_lshl_add_u64 v[242:243], s[26:27], 0, v[150:151]
	ds_read_b128 v[176:179], v190 offset:32768
	ds_read_b128 v[180:183], v190 offset:33792
	ds_read_b128 v[192:195], v190 offset:34816
	ds_read_b128 v[196:199], v190 offset:35840
	ds_read_b128 v[200:203], v190 offset:36864
	ds_read_b128 v[204:207], v190 offset:37888
	ds_read_b128 v[218:221], v190 offset:38912
	ds_read_b128 v[222:225], v190 offset:39936
	global_load_lds_dwordx4 v[242:243], off
	v_lshl_add_u64 v[242:243], s[26:27], 0, v[146:147]
	s_mov_b32 m0, s52
	s_nop 0
	global_load_lds_dwordx4 v[242:243], off
	s_waitcnt vmcnt(8)
	s_waitcnt lgkmcnt(0)
	s_barrier
	s_setprio 1
	s_waitcnt lgkmcnt(0)
	v_mfma_f32_16x16x32_bf16 v[124:127], v[132:135], v[176:179], v[124:127]
	v_mfma_f32_16x16x32_bf16 v[120:123], v[140:143], v[176:179], v[120:123]
	v_mfma_f32_16x16x32_bf16 v[112:115], v[132:135], v[192:195], v[112:115]
	v_mfma_f32_16x16x32_bf16 v[104:107], v[140:143], v[192:195], v[104:107]
	v_mfma_f32_16x16x32_bf16 v[96:99], v[132:135], v[200:203], v[96:99]
	v_mfma_f32_16x16x32_bf16 v[88:91], v[140:143], v[200:203], v[88:91]
	v_mfma_f32_16x16x32_bf16 v[80:83], v[132:135], v[218:221], v[80:83]
	v_mfma_f32_16x16x32_bf16 v[72:75], v[140:143], v[218:221], v[72:75]
	v_mfma_f32_16x16x32_bf16 v[124:127], v[136:139], v[180:183], v[124:127]
	v_mfma_f32_16x16x32_bf16 v[120:123], v[156:159], v[180:183], v[120:123]
	v_mfma_f32_16x16x32_bf16 v[112:115], v[136:139], v[196:199], v[112:115]
	v_mfma_f32_16x16x32_bf16 v[104:107], v[156:159], v[196:199], v[104:107]
	v_mfma_f32_16x16x32_bf16 v[96:99], v[136:139], v[204:207], v[96:99]
	v_mfma_f32_16x16x32_bf16 v[88:91], v[156:159], v[204:207], v[88:91]
	v_mfma_f32_16x16x32_bf16 v[80:83], v[136:139], v[222:225], v[80:83]
	v_mfma_f32_16x16x32_bf16 v[72:75], v[156:159], v[222:225], v[72:75]
	s_setprio 0
	s_setprio 1
	v_mfma_f32_16x16x32_bf16 v[116:119], v[160:163], v[176:179], v[116:119]
	v_mfma_f32_16x16x32_bf16 v[108:111], v[168:171], v[176:179], v[108:111]
	v_mfma_f32_16x16x32_bf16 v[100:103], v[160:163], v[192:195], v[100:103]
	v_mfma_f32_16x16x32_bf16 v[92:95], v[168:171], v[192:195], v[92:95]
	v_mfma_f32_16x16x32_bf16 v[84:87], v[160:163], v[200:203], v[84:87]
	v_mfma_f32_16x16x32_bf16 v[76:79], v[168:171], v[200:203], v[76:79]
	v_mfma_f32_16x16x32_bf16 v[68:71], v[160:163], v[218:221], v[68:71]
	v_mfma_f32_16x16x32_bf16 v[64:67], v[168:171], v[218:221], v[64:67]
	v_mfma_f32_16x16x32_bf16 v[116:119], v[164:167], v[180:183], v[116:119]
	v_mfma_f32_16x16x32_bf16 v[108:111], v[172:175], v[180:183], v[108:111]
	v_mfma_f32_16x16x32_bf16 v[100:103], v[164:167], v[196:199], v[100:103]
	v_mfma_f32_16x16x32_bf16 v[92:95], v[172:175], v[196:199], v[92:95]
	v_mfma_f32_16x16x32_bf16 v[84:87], v[164:167], v[204:207], v[84:87]
	v_mfma_f32_16x16x32_bf16 v[76:79], v[172:175], v[204:207], v[76:79]
	v_mfma_f32_16x16x32_bf16 v[68:71], v[164:167], v[222:225], v[68:71]
	v_mfma_f32_16x16x32_bf16 v[64:67], v[172:175], v[222:225], v[64:67]
	s_setprio 0
	s_barrier
; #define PG8_STAGE(bufoff, gbase, voff) do { _Pragma("unroll") for (int _i = 0; _i < 2; ++_i) \
;         __builtin_amdgcn_global_load_lds((const unsigned*)((const char*)(gbase) + (voff)[_i]), (PG8_LAS unsigned*)(lds + (bufoff) + ldsw + _i * 8192), 16, 0, 0); } while (0)
; #define PG8_LDA(dst, b, h) do { _Pragma("unroll") for (int m = 0; m < 4; ++m) _Pragma("unroll") for (int k = 0; k < 2; ++k) dst[m][k] = *(const PG8_LAS bf16x8*)(lds + PG8_SA(b, h) + aoff + m * 2048 + k * 1024); } while (0)
; #define PG8_MMA(ai, bj, At, Bt) do { __builtin_amdgcn_s_setprio(1); _Pragma("unroll") for (int m = 0; m < 4; ++m) _Pragma("unroll") for (int n = 0; n < 2; ++n) _Pragma("unroll") for (int k = 0; k < 2; ++k) \
;         acc[ai][bj][m][n] = __builtin_amdgcn_mfma_f32_16x16x32_bf16(Bt[n][k], At[m][k], acc[ai][bj][m][n], 0, 0, 0); __builtin_amdgcn_s_setprio(0); } while (0)
; #define PG8_WAIT_V(n) asm volatile("s_waitcnt vmcnt(" #n ")" ::: "memory")
; #define PG8_WAIT_L(n) asm volatile("s_waitcnt lgkmcnt(" #n ")" ::: "memory")
; #define PG8_BAR __builtin_amdgcn_s_barrier()
; #define PG8_SCHED __builtin_amdgcn_sched_barrier(0)
;     ...
;         for (int t = 0; t < nt; t += 2) {
;     ...
;             PG8_LDA(At, 1, 1); PG8_STAGE(PG8_SB(1, 0), b3, voffB); PG8_STAGE(PG8_SB(1, 1), b3 + hstepB, voffB); PG8_STAGE(PG8_SA(1, 0), a3, voffA);
;             PG8_WAIT_V(8); PG8_WAIT_L(0); PG8_BAR; PG8_MMA(1, 0, At, B0); PG8_MMA(1, 1, At, B1); PG8_BAR; PG8_SCHED;
	s_add_i32 s26, s63, s48
	v_lshl_add_u64 v[238:239], v[238:239], 0, s[68:69]
	s_mov_b32 m0, s26
	ds_read_b128 v[176:179], v190 offset:49152
	ds_read_b128 v[180:183], v190 offset:50176
	ds_read_b128 v[192:195], v190 offset:51200
	ds_read_b128 v[196:199], v190 offset:52224
	ds_read_b128 v[200:203], v190 offset:53248
	ds_read_b128 v[204:207], v190 offset:54272
	ds_read_b128 v[218:221], v190 offset:55296
	ds_read_b128 v[222:225], v190 offset:56320
	global_load_lds_dwordx4 v[238:239], off
	s_add_i32 m0, s26, 0x2000
	s_add_u32 s24, s24, 0x40080
	v_lshl_add_u64 v[238:239], v[240:241], 0, s[68:69]
	s_addc_u32 s25, s25, 0
	s_add_i32 s26, s64, s48
	global_load_lds_dwordx4 v[238:239], off
	v_lshl_add_u64 v[238:239], s[24:25], 0, v[148:149]
	s_mov_b32 m0, s26
	s_nop 0
	global_load_lds_dwordx4 v[238:239], off
	v_lshl_add_u64 v[238:239], s[24:25], 0, v[144:145]
	s_add_i32 m0, s26, 0x2000
	s_nop 0
	global_load_lds_dwordx4 v[238:239], off
	v_lshl_add_u64 v[238:239], s[20:21], 0, v[150:151]
	s_mov_b32 m0, s53
	s_nop 0
	global_load_lds_dwordx4 v[238:239], off
	v_lshl_add_u64 v[238:239], s[20:21], 0, v[146:147]
	s_mov_b32 m0, s54
	s_nop 0
	global_load_lds_dwordx4 v[238:239], off
	s_waitcnt vmcnt(8)
	s_waitcnt lgkmcnt(0)
	s_barrier
	s_setprio 1
	s_waitcnt lgkmcnt(0)
	v_mfma_f32_16x16x32_bf16 v[60:63], v[132:135], v[176:179], v[60:63]
	v_mfma_f32_16x16x32_bf16 v[56:59], v[140:143], v[176:179], v[56:59]
	v_mfma_f32_16x16x32_bf16 v[48:51], v[132:135], v[192:195], v[48:51]
	v_mfma_f32_16x16x32_bf16 v[40:43], v[140:143], v[192:195], v[40:43]
	v_mfma_f32_16x16x32_bf16 v[32:35], v[132:135], v[200:203], v[32:35]
	v_mfma_f32_16x16x32_bf16 v[24:27], v[140:143], v[200:203], v[24:27]
	v_mfma_f32_16x16x32_bf16 v[16:19], v[132:135], v[218:221], v[16:19]
	v_mfma_f32_16x16x32_bf16 v[8:11], v[140:143], v[218:221], v[8:11]
	v_mfma_f32_16x16x32_bf16 v[60:63], v[136:139], v[180:183], v[60:63]
	v_mfma_f32_16x16x32_bf16 v[56:59], v[156:159], v[180:183], v[56:59]
	v_mfma_f32_16x16x32_bf16 v[48:51], v[136:139], v[196:199], v[48:51]
	v_mfma_f32_16x16x32_bf16 v[40:43], v[156:159], v[196:199], v[40:43]
	v_mfma_f32_16x16x32_bf16 v[32:35], v[136:139], v[204:207], v[32:35]
	v_mfma_f32_16x16x32_bf16 v[24:27], v[156:159], v[204:207], v[24:27]
	v_mfma_f32_16x16x32_bf16 v[16:19], v[136:139], v[222:225], v[16:19]
	v_mfma_f32_16x16x32_bf16 v[8:11], v[156:159], v[222:225], v[8:11]
	s_setprio 0
	s_setprio 1
	v_mfma_f32_16x16x32_bf16 v[52:55], v[160:163], v[176:179], v[52:55]
	v_mfma_f32_16x16x32_bf16 v[44:47], v[168:171], v[176:179], v[44:47]
	v_mfma_f32_16x16x32_bf16 v[36:39], v[160:163], v[192:195], v[36:39]
	v_mfma_f32_16x16x32_bf16 v[28:31], v[168:171], v[192:195], v[28:31]
	v_mfma_f32_16x16x32_bf16 v[20:23], v[160:163], v[200:203], v[20:23]
	v_mfma_f32_16x16x32_bf16 v[12:15], v[168:171], v[200:203], v[12:15]
	v_mfma_f32_16x16x32_bf16 v[4:7], v[160:163], v[218:221], v[4:7]
	v_mfma_f32_16x16x32_bf16 v[0:3], v[168:171], v[218:221], v[0:3]
	v_mfma_f32_16x16x32_bf16 v[52:55], v[164:167], v[180:183], v[52:55]
	v_mfma_f32_16x16x32_bf16 v[44:47], v[172:175], v[180:183], v[44:47]
	v_mfma_f32_16x16x32_bf16 v[36:39], v[164:167], v[196:199], v[36:39]
	v_mfma_f32_16x16x32_bf16 v[28:31], v[172:175], v[196:199], v[28:31]
	v_mfma_f32_16x16x32_bf16 v[20:23], v[164:167], v[204:207], v[20:23]
	v_mfma_f32_16x16x32_bf16 v[12:15], v[172:175], v[204:207], v[12:15]
	v_mfma_f32_16x16x32_bf16 v[4:7], v[164:167], v[222:225], v[4:7]
	v_mfma_f32_16x16x32_bf16 v[0:3], v[172:175], v[222:225], v[0:3]
	s_setprio 0
	s_barrier
	s_add_i32 s62, s62, 2
	s_add_u32 s2, s2, 0x100
	s_addc_u32 s3, s3, 0
	s_cmp_gt_u32 s62, 13
	s_cbranch_scc0 .LBB0_702
	s_branch .Lpeel_exit_702
	.p2alignl 6, 3212836864

;     __device__ __forceinline__ size_t hstep() const { return (size_t)HALF * K * 2; }
;     __device__ __forceinline__ const char* tile(const Unit& u, int t) const { return A + (size_t)u.pm * 2 * hstep() + (size_t)t * (BK * 2); }
;     __device__ __forceinline__ size_t hstep() const { return (size_t)HALF * 512; }
; #define PG8_STAGE(bufoff, gbase, voff) do { _Pragma("unroll") for (int _i = 0; _i < 2; ++_i) \
;         __builtin_amdgcn_global_load_lds((const unsigned*)((const char*)(gbase) + (voff)[_i]), (PG8_LAS unsigned*)(lds + (bufoff) + ldsw + _i * 8192), 16, 0, 0); } while (0)
; #define PG8_LDA(dst, b, h) do { _Pragma("unroll") for (int m = 0; m < 4; ++m) _Pragma("unroll") for (int k = 0; k < 2; ++k) dst[m][k] = *(const PG8_LAS bf16x8*)(lds + PG8_SA(b, h) + aoff + m * 2048 + k * 1024); } while (0)
; #define PG8_LDB(dst, b, h) do { _Pragma("unroll") for (int n = 0; n < 2; ++n) _Pragma("unroll") for (int k = 0; k < 2; ++k) dst[n][k] = *(const PG8_LAS bf16x8*)(lds + PG8_SB(b, h) + boff + n * 2048 + k * 1024); } while (0)
; #define PG8_WAIT_V(n) asm volatile("s_waitcnt vmcnt(" #n ")" ::: "memory")
; #define PG8_WAIT_L(n) asm volatile("s_waitcnt lgkmcnt(" #n ")" ::: "memory")
; #define PG8_BAR __builtin_amdgcn_s_barrier()
; #define PG8_SCHED __builtin_amdgcn_sched_barrier(0)
;     __device__ __forceinline__ const char* tile(const Unit& u, int t) const { return U + (long)(t >> 2) * xoff + (size_t)u.pn * (1024 * 512) + (size_t)u.pm * 2 * hstep() + (size_t)(t & 3) * (BK * 2); }
;     ...
;         for (int t = 0; t < nt; t += 2) {
;             const bool last = (t == nt - 2);
;             const char* a1 = AS.tile(cur, t + 1);
;             const char* a2 = last ? AS.tile(nu, 0) : AS.tile(cur, t + 2); const char* b2 = last ? nB : cB + (size_t)(t + 2) * kstep;
;             const char* a3 = last ? AS.tile(nu, 1) : AS.tile(cur, t + 3); const char* b3 = b2 + kstep;
;             PG8_LDB(B0, 0, 0); PG8_LDB(B1, 0, 1); PG8_SCHED; PG8_LDA(At, 0, 0); PG8_STAGE(PG8_SA(1, 1), a1 + hstepA, voffA);
;             PG8_WAIT_V(8); PG8_WAIT_L(0); PG8_BAR; PG8_MMA(0, 0, At, B0); PG8_MMA(0, 1, At, B1); PG8_BAR; PG8_SCHED;
;             PG8_LDA(At, 0, 1); PG8_STAGE(PG8_SB(0, 0), b2, voffB); PG8_STAGE(PG8_SB(0, 1), b2 + hstepB, voffB); PG8_STAGE(PG8_SA(0, 0), a2, voffA);
;             PG8_WAIT_V(8); PG8_WAIT_L(0); PG8_BAR; PG8_MMA(1, 0, At, B0); PG8_MMA(1, 1, At, B1); PG8_BAR; PG8_SCHED;
.Lpeel_785:
	s_add_u32 s24, s9, s14
	s_addc_u32 s25, s47, 0
	s_xor_b32 s15, s14, 0x100
	s_add_u32 s15, s9, s15
	s_addc_u32 s20, s47, 0
	s_and_b64 s[18:19], s[16:17], exec
	s_cselect_b32 s21, s49, s20
	s_cselect_b32 s20, s48, s15
	s_add_u32 s15, s52, s14
	s_addc_u32 s18, s53, 0
	s_add_u32 s15, s15, 0x100
	s_addc_u32 s22, s18, 0
	s_and_b64 s[18:19], s[16:17], exec
	s_cselect_b32 s23, s46, s22
	s_cselect_b32 s22, s45, s15
	s_addk_i32 s14, 0x180
	s_and_b32 s14, s14, 0x180
	s_add_u32 s18, s9, s14
	s_addc_u32 s19, s47, 0
	s_and_b64 s[14:15], s[16:17], exec
	s_cselect_b32 s14, s50, s18
	s_cselect_b32 s15, s51, s19
	s_add_i32 s17, 0, 0x10000
	s_add_i32 s62, 0, 0x14000
	s_add_u32 s26, s24, 0x10080
	s_addc_u32 s27, s25, 0
	s_add_i32 s61, s17, s30
	s_add_i32 m0, s31, 0xc000
	s_add_i32 s64, s31, 0xe000
	s_add_i32 s58, s61, 0x2000
	v_add_u32_e32 v140, s17, v159
	s_add_u32 s24, s22, 0x10000
	ds_read_b128 v[162:165], v140
	ds_read_b128 v[166:169], v140 offset:1024
	ds_read_b128 v[170:173], v140 offset:2048
	ds_read_b128 v[174:177], v140 offset:3072
	v_add_u32_e32 v140, s62, v159
	s_addc_u32 s25, s23, 0
	s_add_i32 s60, s62, s30
	ds_read_b128 v[178:181], v140
	ds_read_b128 v[182:185], v140 offset:1024
	ds_read_b128 v[186:189], v140 offset:2048
	ds_read_b128 v[190:193], v140 offset:3072
	s_add_i32 s59, s60, 0x2000
	s_add_i32 s57, 0, 0x18000
	s_add_i32 s56, 0, 0x1c000
	s_add_u32 s18, s20, 0x10000
	s_addc_u32 s19, s21, 0
	s_add_i32 s55, s57, s30
	s_add_i32 s54, s55, 0x2000
	s_add_u32 s16, s22, 0x10080
	s_addc_u32 s17, s23, 0
	s_add_i32 s63, s56, s30
	s_add_i32 s62, s63, 0x2000
	v_lshl_add_u64 v[140:141], s[26:27], 0, v[128:129]
	ds_read_b128 v[194:197], v160
	ds_read_b128 v[198:201], v160 offset:1024
	ds_read_b128 v[202:205], v160 offset:2048
	ds_read_b128 v[218:221], v160 offset:3072
	ds_read_b128 v[222:225], v160 offset:4096
	ds_read_b128 v[238:241], v160 offset:5120
	ds_read_b128 v[242:245], v160 offset:6144
	ds_read_b128 v[246:249], v160 offset:7168
	global_load_lds_dwordx4 v[140:141], off
	v_lshl_add_u64 v[140:141], s[26:27], 0, v[130:131]
	s_mov_b32 m0, s64
	s_nop 0
	global_load_lds_dwordx4 v[140:141], off
	s_waitcnt vmcnt(8)
	s_waitcnt lgkmcnt(0)
	s_barrier
	s_setprio 1
	s_waitcnt lgkmcnt(0)
	v_mfma_f32_16x16x32_bf16 v[124:127], v[162:165], v[194:197], 0
	v_mfma_f32_16x16x32_bf16 v[120:123], v[170:173], v[194:197], 0
	v_mfma_f32_16x16x32_bf16 v[116:119], v[162:165], v[202:205], 0
	v_mfma_f32_16x16x32_bf16 v[108:111], v[170:173], v[202:205], 0
	v_mfma_f32_16x16x32_bf16 v[100:103], v[162:165], v[222:225], 0
	v_mfma_f32_16x16x32_bf16 v[92:95], v[170:173], v[222:225], 0
	v_mfma_f32_16x16x32_bf16 v[84:87], v[162:165], v[242:245], 0
	v_mfma_f32_16x16x32_bf16 v[76:79], v[170:173], v[242:245], 0
	v_mfma_f32_16x16x32_bf16 v[124:127], v[166:169], v[198:201], v[124:127]
	v_mfma_f32_16x16x32_bf16 v[120:123], v[174:177], v[198:201], v[120:123]
	v_mfma_f32_16x16x32_bf16 v[116:119], v[166:169], v[218:221], v[116:119]
	v_mfma_f32_16x16x32_bf16 v[108:111], v[174:177], v[218:221], v[108:111]
	v_mfma_f32_16x16x32_bf16 v[100:103], v[166:169], v[238:241], v[100:103]
	v_mfma_f32_16x16x32_bf16 v[92:95], v[174:177], v[238:241], v[92:95]
	v_mfma_f32_16x16x32_bf16 v[84:87], v[166:169], v[246:249], v[84:87]
	v_mfma_f32_16x16x32_bf16 v[76:79], v[174:177], v[246:249], v[76:79]
	s_setprio 0
	s_setprio 1
	v_mfma_f32_16x16x32_bf16 v[112:115], v[178:181], v[194:197], 0
	v_mfma_f32_16x16x32_bf16 v[104:107], v[186:189], v[194:197], 0
	v_mfma_f32_16x16x32_bf16 v[96:99], v[178:181], v[202:205], 0
	v_mfma_f32_16x16x32_bf16 v[88:91], v[186:189], v[202:205], 0
	v_mfma_f32_16x16x32_bf16 v[80:83], v[178:181], v[222:225], 0
	v_mfma_f32_16x16x32_bf16 v[72:75], v[186:189], v[222:225], 0
	v_mfma_f32_16x16x32_bf16 v[68:71], v[178:181], v[242:245], 0
	v_mfma_f32_16x16x32_bf16 v[64:67], v[186:189], v[242:245], 0
	v_mfma_f32_16x16x32_bf16 v[112:115], v[182:185], v[198:201], v[112:115]
	v_mfma_f32_16x16x32_bf16 v[104:107], v[190:193], v[198:201], v[104:107]
	v_mfma_f32_16x16x32_bf16 v[96:99], v[182:185], v[218:221], v[96:99]
	v_mfma_f32_16x16x32_bf16 v[88:91], v[190:193], v[218:221], v[88:91]
	v_mfma_f32_16x16x32_bf16 v[80:83], v[182:185], v[238:241], v[80:83]
	v_mfma_f32_16x16x32_bf16 v[72:75], v[190:193], v[238:241], v[72:75]
	v_mfma_f32_16x16x32_bf16 v[68:71], v[182:185], v[246:249], v[68:71]
	v_mfma_f32_16x16x32_bf16 v[64:67], v[190:193], v[246:249], v[64:67]
	s_setprio 0
	s_barrier
	s_mov_b32 m0, s61
	v_lshl_add_u64 v[140:141], s[22:23], 0, v[134:135]
	ds_read_b128 v[194:197], v160 offset:16384
	ds_read_b128 v[198:201], v160 offset:17408
	ds_read_b128 v[202:205], v160 offset:18432
	ds_read_b128 v[218:221], v160 offset:19456
	ds_read_b128 v[222:225], v160 offset:20480
	ds_read_b128 v[238:241], v160 offset:21504
	ds_read_b128 v[242:245], v160 offset:22528
	ds_read_b128 v[246:249], v160 offset:23552
	global_load_lds_dwordx4 v[140:141], off
	v_lshl_add_u64 v[206:207], s[22:23], 0, v[132:133]
	s_mov_b32 m0, s58
	v_lshl_add_u64 v[250:251], s[24:25], 0, v[134:135]
	global_load_lds_dwordx4 v[206:207], off
	s_mov_b32 m0, s60
	s_nop 0
	global_load_lds_dwordx4 v[250:251], off
	v_lshl_add_u64 v[250:251], s[24:25], 0, v[132:133]
	s_mov_b32 m0, s59
	s_nop 0
	global_load_lds_dwordx4 v[250:251], off
	v_lshl_add_u64 v[250:251], s[20:21], 0, v[128:129]
	s_mov_b32 m0, s31
	s_nop 0
	global_load_lds_dwordx4 v[250:251], off
	v_lshl_add_u64 v[250:251], s[20:21], 0, v[130:131]
	s_mov_b32 m0, s35
	s_nop 0
	global_load_lds_dwordx4 v[250:251], off
	s_waitcnt vmcnt(8)
	s_waitcnt lgkmcnt(0)
	s_barrier
; #define PG8_STAGE(bufoff, gbase, voff) do { _Pragma("unroll") for (int _i = 0; _i < 2; ++_i) \
;         __builtin_amdgcn_global_load_lds((const unsigned*)((const char*)(gbase) + (voff)[_i]), (PG8_LAS unsigned*)(lds + (bufoff) + ldsw + _i * 8192), 16, 0, 0); } while (0)
; #define PG8_LDA(dst, b, h) do { _Pragma("unroll") for (int m = 0; m < 4; ++m) _Pragma("unroll") for (int k = 0; k < 2; ++k) dst[m][k] = *(const PG8_LAS bf16x8*)(lds + PG8_SA(b, h) + aoff + m * 2048 + k * 1024); } while (0)
; #define PG8_LDB(dst, b, h) do { _Pragma("unroll") for (int n = 0; n < 2; ++n) _Pragma("unroll") for (int k = 0; k < 2; ++k) dst[n][k] = *(const PG8_LAS bf16x8*)(lds + PG8_SB(b, h) + boff + n * 2048 + k * 1024); } while (0)
; #define PG8_MMA(ai, bj, At, Bt) do { __builtin_amdgcn_s_setprio(1); _Pragma("unroll") for (int m = 0; m < 4; ++m) _Pragma("unroll") for (int n = 0; n < 2; ++n) _Pragma("unroll") for (int k = 0; k < 2; ++k) \
;         acc[ai][bj][m][n] = __builtin_amdgcn_mfma_f32_16x16x32_bf16(Bt[n][k], At[m][k], acc[ai][bj][m][n], 0, 0, 0); __builtin_amdgcn_s_setprio(0); } while (0)
; #define PG8_WAIT_V(n) asm volatile("s_waitcnt vmcnt(" #n ")" ::: "memory")
; #define PG8_WAIT_L(n) asm volatile("s_waitcnt lgkmcnt(" #n ")" ::: "memory")
; #define PG8_BAR __builtin_amdgcn_s_barrier()
; #define PG8_SCHED __builtin_amdgcn_sched_barrier(0)
;     ...
;             PG8_WAIT_V(8); PG8_WAIT_L(0); PG8_BAR; PG8_MMA(1, 0, At, B0); PG8_MMA(1, 1, At, B1); PG8_BAR; PG8_SCHED;
;             PG8_LDB(B0, 1, 0); PG8_LDB(B1, 1, 1); PG8_SCHED; PG8_LDA(At, 1, 0); PG8_STAGE(PG8_SA(0, 1), a2 + hstepA, voffA);
;             PG8_WAIT_V(8); PG8_WAIT_L(0); PG8_BAR; PG8_MMA(0, 0, At, B0); PG8_MMA(0, 1, At, B1); PG8_BAR; PG8_SCHED;
	s_setprio 1
	s_waitcnt lgkmcnt(0)
	v_mfma_f32_16x16x32_bf16 v[60:63], v[162:165], v[194:197], 0
	v_mfma_f32_16x16x32_bf16 v[56:59], v[170:173], v[194:197], 0
	v_mfma_f32_16x16x32_bf16 v[52:55], v[162:165], v[202:205], 0
	v_mfma_f32_16x16x32_bf16 v[44:47], v[170:173], v[202:205], 0
	v_mfma_f32_16x16x32_bf16 v[36:39], v[162:165], v[222:225], 0
	v_mfma_f32_16x16x32_bf16 v[28:31], v[170:173], v[222:225], 0
	v_mfma_f32_16x16x32_bf16 v[20:23], v[162:165], v[242:245], 0
	v_mfma_f32_16x16x32_bf16 v[12:15], v[170:173], v[242:245], 0
	v_mfma_f32_16x16x32_bf16 v[60:63], v[166:169], v[198:201], v[60:63]
	v_mfma_f32_16x16x32_bf16 v[56:59], v[174:177], v[198:201], v[56:59]
	v_mfma_f32_16x16x32_bf16 v[52:55], v[166:169], v[218:221], v[52:55]
	v_mfma_f32_16x16x32_bf16 v[44:47], v[174:177], v[218:221], v[44:47]
	v_mfma_f32_16x16x32_bf16 v[36:39], v[166:169], v[238:241], v[36:39]
	v_mfma_f32_16x16x32_bf16 v[28:31], v[174:177], v[238:241], v[28:31]
	v_mfma_f32_16x16x32_bf16 v[20:23], v[166:169], v[246:249], v[20:23]
	v_mfma_f32_16x16x32_bf16 v[12:15], v[174:177], v[246:249], v[12:15]
	s_setprio 0
	s_setprio 1
	v_mfma_f32_16x16x32_bf16 v[48:51], v[178:181], v[194:197], 0
	v_mfma_f32_16x16x32_bf16 v[40:43], v[186:189], v[194:197], 0
	v_mfma_f32_16x16x32_bf16 v[32:35], v[178:181], v[202:205], 0
	v_mfma_f32_16x16x32_bf16 v[24:27], v[186:189], v[202:205], 0
	v_mfma_f32_16x16x32_bf16 v[16:19], v[178:181], v[222:225], 0
	v_mfma_f32_16x16x32_bf16 v[8:11], v[186:189], v[222:225], 0
	v_mfma_f32_16x16x32_bf16 v[4:7], v[178:181], v[242:245], 0
	v_mfma_f32_16x16x32_bf16 v[0:3], v[186:189], v[242:245], 0
	v_mfma_f32_16x16x32_bf16 v[48:51], v[182:185], v[198:201], v[48:51]
	v_mfma_f32_16x16x32_bf16 v[40:43], v[190:193], v[198:201], v[40:43]
	v_mfma_f32_16x16x32_bf16 v[32:35], v[182:185], v[218:221], v[32:35]
	v_mfma_f32_16x16x32_bf16 v[24:27], v[190:193], v[218:221], v[24:27]
	v_mfma_f32_16x16x32_bf16 v[16:19], v[182:185], v[238:241], v[16:19]
	v_mfma_f32_16x16x32_bf16 v[8:11], v[190:193], v[238:241], v[8:11]
	v_mfma_f32_16x16x32_bf16 v[4:7], v[182:185], v[246:249], v[4:7]
	v_mfma_f32_16x16x32_bf16 v[0:3], v[190:193], v[246:249], v[0:3]
	s_setprio 0
	s_barrier
	v_add_u32_e32 v161, s57, v159
	ds_read_b128 v[162:165], v161
	ds_read_b128 v[166:169], v161 offset:1024
	ds_read_b128 v[170:173], v161 offset:2048
	ds_read_b128 v[174:177], v161 offset:3072
	v_add_u32_e32 v161, s56, v159
	ds_read_b128 v[178:181], v161
	ds_read_b128 v[182:185], v161 offset:1024
	ds_read_b128 v[186:189], v161 offset:2048
	ds_read_b128 v[190:193], v161 offset:3072
	s_mov_b32 m0, s36
	v_lshl_add_u64 v[250:251], s[18:19], 0, v[128:129]
	ds_read_b128 v[194:197], v160 offset:32768
	ds_read_b128 v[198:201], v160 offset:33792
	ds_read_b128 v[202:205], v160 offset:34816
	ds_read_b128 v[218:221], v160 offset:35840
	ds_read_b128 v[222:225], v160 offset:36864
	ds_read_b128 v[238:241], v160 offset:37888
	ds_read_b128 v[242:245], v160 offset:38912
	ds_read_b128 v[246:249], v160 offset:39936
	global_load_lds_dwordx4 v[250:251], off
	v_lshl_add_u64 v[250:251], s[18:19], 0, v[130:131]
	s_mov_b32 m0, s37
	s_nop 0
	global_load_lds_dwordx4 v[250:251], off
	s_waitcnt vmcnt(8)
	s_waitcnt lgkmcnt(0)
	s_barrier
	s_setprio 1
	s_waitcnt lgkmcnt(0)
	v_mfma_f32_16x16x32_bf16 v[124:127], v[162:165], v[194:197], v[124:127]
	v_mfma_f32_16x16x32_bf16 v[120:123], v[170:173], v[194:197], v[120:123]
	v_mfma_f32_16x16x32_bf16 v[116:119], v[162:165], v[202:205], v[116:119]
	v_mfma_f32_16x16x32_bf16 v[108:111], v[170:173], v[202:205], v[108:111]
	v_mfma_f32_16x16x32_bf16 v[100:103], v[162:165], v[222:225], v[100:103]
	v_mfma_f32_16x16x32_bf16 v[92:95], v[170:173], v[222:225], v[92:95]
	v_mfma_f32_16x16x32_bf16 v[84:87], v[162:165], v[242:245], v[84:87]
	v_mfma_f32_16x16x32_bf16 v[76:79], v[170:173], v[242:245], v[76:79]
	v_mfma_f32_16x16x32_bf16 v[124:127], v[166:169], v[198:201], v[124:127]
	v_mfma_f32_16x16x32_bf16 v[120:123], v[174:177], v[198:201], v[120:123]
	v_mfma_f32_16x16x32_bf16 v[116:119], v[166:169], v[218:221], v[116:119]
	v_mfma_f32_16x16x32_bf16 v[108:111], v[174:177], v[218:221], v[108:111]
	v_mfma_f32_16x16x32_bf16 v[100:103], v[166:169], v[238:241], v[100:103]
	v_mfma_f32_16x16x32_bf16 v[92:95], v[174:177], v[238:241], v[92:95]
	v_mfma_f32_16x16x32_bf16 v[84:87], v[166:169], v[246:249], v[84:87]
	v_mfma_f32_16x16x32_bf16 v[76:79], v[174:177], v[246:249], v[76:79]
	s_setprio 0
	s_setprio 1
	v_mfma_f32_16x16x32_bf16 v[112:115], v[178:181], v[194:197], v[112:115]
	v_mfma_f32_16x16x32_bf16 v[104:107], v[186:189], v[194:197], v[104:107]
	v_mfma_f32_16x16x32_bf16 v[96:99], v[178:181], v[202:205], v[96:99]
	v_mfma_f32_16x16x32_bf16 v[88:91], v[186:189], v[202:205], v[88:91]
	v_mfma_f32_16x16x32_bf16 v[80:83], v[178:181], v[222:225], v[80:83]
	v_mfma_f32_16x16x32_bf16 v[72:75], v[186:189], v[222:225], v[72:75]
	v_mfma_f32_16x16x32_bf16 v[68:71], v[178:181], v[242:245], v[68:71]
	v_mfma_f32_16x16x32_bf16 v[64:67], v[186:189], v[242:245], v[64:67]
	v_mfma_f32_16x16x32_bf16 v[112:115], v[182:185], v[198:201], v[112:115]
	v_mfma_f32_16x16x32_bf16 v[104:107], v[190:193], v[198:201], v[104:107]
	v_mfma_f32_16x16x32_bf16 v[96:99], v[182:185], v[218:221], v[96:99]
	v_mfma_f32_16x16x32_bf16 v[88:91], v[190:193], v[218:221], v[88:91]
	v_mfma_f32_16x16x32_bf16 v[80:83], v[182:185], v[238:241], v[80:83]
	v_mfma_f32_16x16x32_bf16 v[72:75], v[190:193], v[238:241], v[72:75]
	v_mfma_f32_16x16x32_bf16 v[68:71], v[182:185], v[246:249], v[68:71]
	v_mfma_f32_16x16x32_bf16 v[64:67], v[190:193], v[246:249], v[64:67]
	s_setprio 0
	s_barrier
; #define PG8_STAGE(bufoff, gbase, voff) do { _Pragma("unroll") for (int _i = 0; _i < 2; ++_i) \
;         __builtin_amdgcn_global_load_lds((const unsigned*)((const char*)(gbase) + (voff)[_i]), (PG8_LAS unsigned*)(lds + (bufoff) + ldsw + _i * 8192), 16, 0, 0); } while (0)
; #define PG8_LDA(dst, b, h) do { _Pragma("unroll") for (int m = 0; m < 4; ++m) _Pragma("unroll") for (int k = 0; k < 2; ++k) dst[m][k] = *(const PG8_LAS bf16x8*)(lds + PG8_SA(b, h) + aoff + m * 2048 + k * 1024); } while (0)
; #define PG8_MMA(ai, bj, At, Bt) do { __builtin_amdgcn_s_setprio(1); _Pragma("unroll") for (int m = 0; m < 4; ++m) _Pragma("unroll") for (int n = 0; n < 2; ++n) _Pragma("unroll") for (int k = 0; k < 2; ++k) \
;         acc[ai][bj][m][n] = __builtin_amdgcn_mfma_f32_16x16x32_bf16(Bt[n][k], At[m][k], acc[ai][bj][m][n], 0, 0, 0); __builtin_amdgcn_s_setprio(0); } while (0)
; #define PG8_WAIT_V(n) asm volatile("s_waitcnt vmcnt(" #n ")" ::: "memory")
; #define PG8_WAIT_L(n) asm volatile("s_waitcnt lgkmcnt(" #n ")" ::: "memory")
; #define PG8_BAR __builtin_amdgcn_s_barrier()
; #define PG8_SCHED __builtin_amdgcn_sched_barrier(0)
;     ...
;         for (int t = 0; t < nt; t += 2) {
;     ...
;             PG8_LDA(At, 1, 1); PG8_STAGE(PG8_SB(1, 0), b3, voffB); PG8_STAGE(PG8_SB(1, 1), b3 + hstepB, voffB); PG8_STAGE(PG8_SA(1, 0), a3, voffA);
;             PG8_WAIT_V(8); PG8_WAIT_L(0); PG8_BAR; PG8_MMA(1, 0, At, B0); PG8_MMA(1, 1, At, B1); PG8_BAR; PG8_SCHED;
	s_mov_b32 m0, s55
	v_lshl_add_u64 v[140:141], v[140:141], 0, s[66:67]
	ds_read_b128 v[194:197], v160 offset:49152
	ds_read_b128 v[198:201], v160 offset:50176
	ds_read_b128 v[202:205], v160 offset:51200
	ds_read_b128 v[218:221], v160 offset:52224
	ds_read_b128 v[222:225], v160 offset:53248
	ds_read_b128 v[238:241], v160 offset:54272
	ds_read_b128 v[242:245], v160 offset:55296
	ds_read_b128 v[246:249], v160 offset:56320
	global_load_lds_dwordx4 v[140:141], off
	v_lshl_add_u64 v[140:141], v[206:207], 0, s[66:67]
	s_mov_b32 m0, s54
	s_nop 0
	global_load_lds_dwordx4 v[140:141], off
	v_lshl_add_u64 v[140:141], s[16:17], 0, v[134:135]
	s_mov_b32 m0, s63
	s_nop 0
	global_load_lds_dwordx4 v[140:141], off
	v_lshl_add_u64 v[140:141], s[16:17], 0, v[132:133]
	s_mov_b32 m0, s62
	s_nop 0
	global_load_lds_dwordx4 v[140:141], off
	v_lshl_add_u64 v[140:141], s[14:15], 0, v[128:129]
	s_mov_b32 m0, s40
	s_nop 0
	global_load_lds_dwordx4 v[140:141], off
	v_lshl_add_u64 v[140:141], s[14:15], 0, v[130:131]
	s_mov_b32 m0, s41
	s_nop 0
	global_load_lds_dwordx4 v[140:141], off
	s_waitcnt vmcnt(8)
	s_waitcnt lgkmcnt(0)
	s_barrier
	s_setprio 1
	s_waitcnt lgkmcnt(0)
	v_mfma_f32_16x16x32_bf16 v[60:63], v[162:165], v[194:197], v[60:63]
	v_mfma_f32_16x16x32_bf16 v[56:59], v[170:173], v[194:197], v[56:59]
	v_mfma_f32_16x16x32_bf16 v[52:55], v[162:165], v[202:205], v[52:55]
	v_mfma_f32_16x16x32_bf16 v[44:47], v[170:173], v[202:205], v[44:47]
	v_mfma_f32_16x16x32_bf16 v[36:39], v[162:165], v[222:225], v[36:39]
	v_mfma_f32_16x16x32_bf16 v[28:31], v[170:173], v[222:225], v[28:31]
	v_mfma_f32_16x16x32_bf16 v[20:23], v[162:165], v[242:245], v[20:23]
	v_mfma_f32_16x16x32_bf16 v[12:15], v[170:173], v[242:245], v[12:15]
	v_mfma_f32_16x16x32_bf16 v[60:63], v[166:169], v[198:201], v[60:63]
	v_mfma_f32_16x16x32_bf16 v[56:59], v[174:177], v[198:201], v[56:59]
	v_mfma_f32_16x16x32_bf16 v[52:55], v[166:169], v[218:221], v[52:55]
	v_mfma_f32_16x16x32_bf16 v[44:47], v[174:177], v[218:221], v[44:47]
	v_mfma_f32_16x16x32_bf16 v[36:39], v[166:169], v[238:241], v[36:39]
	v_mfma_f32_16x16x32_bf16 v[28:31], v[174:177], v[238:241], v[28:31]
	v_mfma_f32_16x16x32_bf16 v[20:23], v[166:169], v[246:249], v[20:23]
	v_mfma_f32_16x16x32_bf16 v[12:15], v[174:177], v[246:249], v[12:15]
	s_setprio 0
	s_setprio 1
	v_mfma_f32_16x16x32_bf16 v[48:51], v[178:181], v[194:197], v[48:51]
	v_mfma_f32_16x16x32_bf16 v[40:43], v[186:189], v[194:197], v[40:43]
	v_mfma_f32_16x16x32_bf16 v[32:35], v[178:181], v[202:205], v[32:35]
	v_mfma_f32_16x16x32_bf16 v[24:27], v[186:189], v[202:205], v[24:27]
	v_mfma_f32_16x16x32_bf16 v[16:19], v[178:181], v[222:225], v[16:19]
	v_mfma_f32_16x16x32_bf16 v[8:11], v[186:189], v[222:225], v[8:11]
	v_mfma_f32_16x16x32_bf16 v[4:7], v[178:181], v[242:245], v[4:7]
	v_mfma_f32_16x16x32_bf16 v[0:3], v[186:189], v[242:245], v[0:3]
	v_mfma_f32_16x16x32_bf16 v[48:51], v[182:185], v[198:201], v[48:51]
	v_mfma_f32_16x16x32_bf16 v[40:43], v[190:193], v[198:201], v[40:43]
	v_mfma_f32_16x16x32_bf16 v[32:35], v[182:185], v[218:221], v[32:35]
	v_mfma_f32_16x16x32_bf16 v[24:27], v[190:193], v[218:221], v[24:27]
	v_mfma_f32_16x16x32_bf16 v[16:19], v[182:185], v[238:241], v[16:19]
	v_mfma_f32_16x16x32_bf16 v[8:11], v[190:193], v[238:241], v[8:11]
	v_mfma_f32_16x16x32_bf16 v[4:7], v[182:185], v[246:249], v[4:7]
	v_mfma_f32_16x16x32_bf16 v[0:3], v[190:193], v[246:249], v[0:3]
	s_setprio 0
	s_barrier
	s_andn2_b64 vcc, exec, s[12:13]
	s_mov_b64 s[16:17], -1
	s_mov_b64 s[12:13], 0
	s_movk_i32 s14, 0x100
	s_cbranch_vccz .LBB0_785
	s_branch .Lpeel_exit_785
	.p2alignl 6, 3212836864
